# speedup vs baseline: 1.0120x; 1.0120x over previous
; #define WAIT_V(n) asm volatile("s_waitcnt vmcnt(" #n ")" ::: "memory")
; #define WAIT_L(n) asm volatile("s_waitcnt lgkmcnt(" #n ")" ::: "memory")
; #define BAR __builtin_amdgcn_s_barrier()
; #define SCHED __builtin_amdgcn_sched_barrier(0)
; #define STAGE_A(b, h, kt)                                        \
;   do {                                                           \
;     const char* _g = Ab + (h) * halfK + (long)(kt) * 128;        \
;     GLDS2(_g, (unsigned)(((b) * 2 + (h)) * 16384));              \
;   } while (0)
; #define STAGE_B(b, h, kt)                                        \
;   do {                                                           \
;     const char* _g = Bb + (h) * halfK + (long)(kt) * 128;        \
;     GLDS2(_g, (unsigned)(65536 + ((b) * 2 + (h)) * 16384));      \
;   } while (0)
; #define LDA(dst, b, h)                                                                                   \
;   _Pragma("unroll") for (int m = 0; m < 4; ++m) _Pragma("unroll") for (int k = 0; k < 2; ++k) dst[m][k] = \
;       *reinterpret_cast<const bf16x8*>(aRd + ((b) * 2 + (h)) * 16384 + m * 2048 + k * 1024)
; #define LDB(dst, b, h)                                                                                   \
;   _Pragma("unroll") for (int n = 0; n < 2; ++n) _Pragma("unroll") for (int k = 0; k < 2; ++k) dst[n][k] = \
;       *reinterpret_cast<const bf16x8*>(bRd + ((b) * 2 + (h)) * 16384 + n * 2048 + k * 1024)
; template <int EPI> ...
;     ...
;     LDB(B0, 0, 0);
;     SCHED;
;     LDA(At, 0, 0);
;     STAGE_A(1, 1, t + 1);
;     WAIT_L(8);
;     BAR;
;     WAIT_L(0);
;     MMA(0, 0, At, B0);
;     BAR;
;     SCHED;
;     LDB(B1, 0, 1);
;     STAGE_B(0, 0, t + 2);
;     BAR;
;     WAIT_L(0);
;     MMA(0, 1, At, B1);
;     BAR;
;     LDA(At, 0, 1);
;     STAGE_A(0, 0, t + 2);
;     BAR;
;     WAIT_L(0);
;     MMA(1, 0, At, B0);
;     BAR;
;     SCHED;
;     STAGE_B(0, 1, t + 2);
;     WAIT_V(6);
;     BAR;
.LBB0_114:
	ds_read_b128 v[138:141], v137
	ds_read_b128 v[142:145], v137 offset:1024
	ds_read_b128 v[146:149], v137 offset:2048
	ds_read_b128 v[150:153], v137 offset:3072
	ds_read_b128 v[154:157], v136
	ds_read_b128 v[158:161], v136 offset:1024
	ds_read_b128 v[162:165], v136 offset:2048
	ds_read_b128 v[166:169], v136 offset:3072
	ds_read_b128 v[170:173], v136 offset:4096
	ds_read_b128 v[174:177], v136 offset:5120
	ds_read_b128 v[178:181], v136 offset:6144
	ds_read_b128 v[182:185], v136 offset:7168
	s_add_u32 s22, s11, s12
	s_addc_u32 s23, s37, s13
	s_add_u32 s74, s22, 0x80
	s_addc_u32 s75, s23, 0
	s_mov_b32 m0, s77
	s_nop 0
	global_load_lds_dwordx4 v132, s[74:75]
	s_nop 0
	s_mov_b32 m0, s64
	s_nop 0
	global_load_lds_dwordx4 v130, s[74:75]
	s_waitcnt lgkmcnt(8)
	s_barrier
	s_waitcnt lgkmcnt(0)
	s_setprio 1
	v_mfma_f32_16x16x32_bf16 v[126:129], v[138:141], v[154:157], v[126:129]
	v_mfma_f32_16x16x32_bf16 v[126:129], v[142:145], v[158:161], v[126:129]
	v_mfma_f32_16x16x32_bf16 v[122:125], v[146:149], v[154:157], v[122:125]
	v_mfma_f32_16x16x32_bf16 v[122:125], v[150:153], v[158:161], v[122:125]
	v_mfma_f32_16x16x32_bf16 v[118:121], v[138:141], v[162:165], v[118:121]
	v_mfma_f32_16x16x32_bf16 v[118:121], v[142:145], v[166:169], v[118:121]
	v_mfma_f32_16x16x32_bf16 v[114:117], v[146:149], v[162:165], v[114:117]
	v_mfma_f32_16x16x32_bf16 v[114:117], v[150:153], v[166:169], v[114:117]
	v_mfma_f32_16x16x32_bf16 v[110:113], v[138:141], v[170:173], v[110:113]
	v_mfma_f32_16x16x32_bf16 v[110:113], v[142:145], v[174:177], v[110:113]
	v_mfma_f32_16x16x32_bf16 v[106:109], v[146:149], v[170:173], v[106:109]
	v_mfma_f32_16x16x32_bf16 v[106:109], v[150:153], v[174:177], v[106:109]
	v_mfma_f32_16x16x32_bf16 v[102:105], v[138:141], v[178:181], v[102:105]
	v_mfma_f32_16x16x32_bf16 v[102:105], v[142:145], v[182:185], v[102:105]
	v_mfma_f32_16x16x32_bf16 v[98:101], v[146:149], v[178:181], v[98:101]
	v_mfma_f32_16x16x32_bf16 v[98:101], v[150:153], v[182:185], v[98:101]
	s_setprio 0
	s_barrier
	ds_read_b128 v[186:189], v137 offset:16384
	ds_read_b128 v[196:199], v137 offset:17408
	ds_read_b128 v[212:215], v137 offset:18432
	ds_read_b128 v[220:223], v137 offset:19456
	s_add_u32 s49, s98, s12
	s_addc_u32 s54, s99, s13
	s_add_u32 s74, s49, 0x100
	s_addc_u32 s75, s54, 0
	s_mov_b32 m0, s20
	s_nop 0
	global_load_lds_dwordx4 v132, s[74:75]
	s_nop 0
	s_mov_b32 m0, s21
	s_nop 0
	global_load_lds_dwordx4 v130, s[74:75]
	s_barrier
	s_waitcnt lgkmcnt(0)
	s_setprio 1
	v_mfma_f32_16x16x32_bf16 v[94:97], v[186:189], v[154:157], v[94:97]
	v_mfma_f32_16x16x32_bf16 v[94:97], v[196:199], v[158:161], v[94:97]
	v_mfma_f32_16x16x32_bf16 v[90:93], v[212:215], v[154:157], v[90:93]
	v_mfma_f32_16x16x32_bf16 v[90:93], v[220:223], v[158:161], v[90:93]
	v_mfma_f32_16x16x32_bf16 v[86:89], v[186:189], v[162:165], v[86:89]
	v_mfma_f32_16x16x32_bf16 v[86:89], v[196:199], v[166:169], v[86:89]
	v_mfma_f32_16x16x32_bf16 v[82:85], v[212:215], v[162:165], v[82:85]
	v_mfma_f32_16x16x32_bf16 v[82:85], v[220:223], v[166:169], v[82:85]
	v_mfma_f32_16x16x32_bf16 v[78:81], v[186:189], v[170:173], v[78:81]
	v_mfma_f32_16x16x32_bf16 v[78:81], v[196:199], v[174:177], v[78:81]
	v_mfma_f32_16x16x32_bf16 v[74:77], v[212:215], v[170:173], v[74:77]
	v_mfma_f32_16x16x32_bf16 v[74:77], v[220:223], v[174:177], v[74:77]
	v_mfma_f32_16x16x32_bf16 v[70:73], v[186:189], v[178:181], v[70:73]
	v_mfma_f32_16x16x32_bf16 v[70:73], v[196:199], v[182:185], v[70:73]
	v_mfma_f32_16x16x32_bf16 v[66:69], v[212:215], v[178:181], v[66:69]
	v_mfma_f32_16x16x32_bf16 v[66:69], v[220:223], v[182:185], v[66:69]
	s_setprio 0
	s_barrier
	ds_read_b128 v[154:157], v136 offset:16384
	ds_read_b128 v[158:161], v136 offset:17408
	ds_read_b128 v[162:165], v136 offset:18432
	ds_read_b128 v[166:169], v136 offset:19456
	ds_read_b128 v[170:173], v136 offset:20480
	ds_read_b128 v[174:177], v136 offset:21504
	ds_read_b128 v[178:181], v136 offset:22528
	ds_read_b128 v[182:185], v136 offset:23552
	s_add_u32 s60, s96, s12
	s_addc_u32 s68, s97, s13
	s_add_u32 s74, s60, 0x100
	s_addc_u32 s75, s68, 0
	s_mov_b32 m0, s2
	s_nop 0
	global_load_lds_dwordx4 v132, s[74:75]
	s_nop 0
	s_mov_b32 m0, s38
	s_nop 0
	global_load_lds_dwordx4 v130, s[74:75]
	s_barrier
	s_waitcnt lgkmcnt(0)
	s_setprio 1
	v_mfma_f32_16x16x32_bf16 v[62:65], v[138:141], v[154:157], v[62:65]
	v_mfma_f32_16x16x32_bf16 v[62:65], v[142:145], v[158:161], v[62:65]
	v_mfma_f32_16x16x32_bf16 v[58:61], v[146:149], v[154:157], v[58:61]
	v_mfma_f32_16x16x32_bf16 v[58:61], v[150:153], v[158:161], v[58:61]
	v_mfma_f32_16x16x32_bf16 v[54:57], v[138:141], v[162:165], v[54:57]
	v_mfma_f32_16x16x32_bf16 v[54:57], v[142:145], v[166:169], v[54:57]
	v_mfma_f32_16x16x32_bf16 v[50:53], v[146:149], v[162:165], v[50:53]
	v_mfma_f32_16x16x32_bf16 v[50:53], v[150:153], v[166:169], v[50:53]
	v_mfma_f32_16x16x32_bf16 v[46:49], v[138:141], v[170:173], v[46:49]
	v_mfma_f32_16x16x32_bf16 v[46:49], v[142:145], v[174:177], v[46:49]
	v_mfma_f32_16x16x32_bf16 v[42:45], v[146:149], v[170:173], v[42:45]
	v_mfma_f32_16x16x32_bf16 v[42:45], v[150:153], v[174:177], v[42:45]
	v_mfma_f32_16x16x32_bf16 v[38:41], v[138:141], v[178:181], v[38:41]
	v_mfma_f32_16x16x32_bf16 v[38:41], v[142:145], v[182:185], v[38:41]
	v_mfma_f32_16x16x32_bf16 v[34:37], v[146:149], v[178:181], v[34:37]
	v_mfma_f32_16x16x32_bf16 v[34:37], v[150:153], v[182:185], v[34:37]
	s_setprio 0
	s_barrier
	s_add_u32 s69, s7, s12
	s_addc_u32 s76, s8, s13
	s_add_u32 s74, s69, 0x100
	s_addc_u32 s75, s76, 0
	s_mov_b32 m0, s39
	s_nop 0
	global_load_lds_dwordx4 v132, s[74:75]
	s_nop 0
	s_mov_b32 m0, s28
	s_nop 0
	global_load_lds_dwordx4 v130, s[74:75]
	s_waitcnt vmcnt(6)
	s_barrier
; #define WAIT_L(n) asm volatile("s_waitcnt lgkmcnt(" #n ")" ::: "memory")
; #define BAR __builtin_amdgcn_s_barrier()
; #define SCHED __builtin_amdgcn_sched_barrier(0)
; #define STAGE_A(b, h, kt)                                        \
;   do {                                                           \
;     const char* _g = Ab + (h) * halfK + (long)(kt) * 128;        \
;     GLDS2(_g, (unsigned)(((b) * 2 + (h)) * 16384));              \
;   } while (0)
; #define STAGE_B(b, h, kt)                                        \
;   do {                                                           \
;     const char* _g = Bb + (h) * halfK + (long)(kt) * 128;        \
;     GLDS2(_g, (unsigned)(65536 + ((b) * 2 + (h)) * 16384));      \
;   } while (0)
; #define LDA(dst, b, h)                                                                                   \
;   _Pragma("unroll") for (int m = 0; m < 4; ++m) _Pragma("unroll") for (int k = 0; k < 2; ++k) dst[m][k] = \
;       *reinterpret_cast<const bf16x8*>(aRd + ((b) * 2 + (h)) * 16384 + m * 2048 + k * 1024)
; #define LDB(dst, b, h)                                                                                   \
;   _Pragma("unroll") for (int n = 0; n < 2; ++n) _Pragma("unroll") for (int k = 0; k < 2; ++k) dst[n][k] = \
;       *reinterpret_cast<const bf16x8*>(bRd + ((b) * 2 + (h)) * 16384 + n * 2048 + k * 1024)
; template <int EPI> ...
;     ...
;     MMA(1, 1, At, B1);
;     BAR;
;     LDB(B0, 1, 0);
;     SCHED;
;     LDA(At, 1, 0);
;     STAGE_A(0, 1, t + 2);
;     WAIT_L(8);
;     BAR;
;     WAIT_L(0);
;     MMA(0, 0, At, B0);
;     BAR;
;     SCHED;
;     LDB(B1, 1, 1);
;     STAGE_B(1, 0, t + 3);
;     BAR;
;     WAIT_L(0);
;     MMA(0, 1, At, B1);
;     BAR;
;     LDA(At, 1, 1);
;     STAGE_A(1, 0, t + 3);
;     BAR;
;     WAIT_L(0);
;     MMA(1, 0, At, B0);
;     BAR;
;     SCHED;
;     STAGE_B(1, 1, t + 3);
	s_setprio 1
	v_mfma_f32_16x16x32_bf16 v[30:33], v[186:189], v[154:157], v[30:33]
	v_mfma_f32_16x16x32_bf16 v[30:33], v[196:199], v[158:161], v[30:33]
	v_mfma_f32_16x16x32_bf16 v[26:29], v[212:215], v[154:157], v[26:29]
	v_mfma_f32_16x16x32_bf16 v[26:29], v[220:223], v[158:161], v[26:29]
	v_mfma_f32_16x16x32_bf16 v[22:25], v[186:189], v[162:165], v[22:25]
	v_mfma_f32_16x16x32_bf16 v[22:25], v[196:199], v[166:169], v[22:25]
	v_mfma_f32_16x16x32_bf16 v[18:21], v[212:215], v[162:165], v[18:21]
	v_mfma_f32_16x16x32_bf16 v[18:21], v[220:223], v[166:169], v[18:21]
	v_mfma_f32_16x16x32_bf16 v[14:17], v[186:189], v[170:173], v[14:17]
	v_mfma_f32_16x16x32_bf16 v[14:17], v[196:199], v[174:177], v[14:17]
	v_mfma_f32_16x16x32_bf16 v[10:13], v[212:215], v[170:173], v[10:13]
	v_mfma_f32_16x16x32_bf16 v[10:13], v[220:223], v[174:177], v[10:13]
	v_mfma_f32_16x16x32_bf16 v[6:9], v[186:189], v[178:181], v[6:9]
	v_mfma_f32_16x16x32_bf16 v[6:9], v[196:199], v[182:185], v[6:9]
	v_mfma_f32_16x16x32_bf16 v[2:5], v[212:215], v[178:181], v[2:5]
	v_mfma_f32_16x16x32_bf16 v[2:5], v[220:223], v[182:185], v[2:5]
	s_setprio 0
	s_barrier
	ds_read_b128 v[138:141], v137 offset:32768
	ds_read_b128 v[142:145], v137 offset:33792
	ds_read_b128 v[146:149], v137 offset:34816
	ds_read_b128 v[150:153], v137 offset:35840
	ds_read_b128 v[154:157], v136 offset:32768
	ds_read_b128 v[158:161], v136 offset:33792
	ds_read_b128 v[162:165], v136 offset:34816
	ds_read_b128 v[166:169], v136 offset:35840
	ds_read_b128 v[170:173], v136 offset:36864
	ds_read_b128 v[174:177], v136 offset:37888
	ds_read_b128 v[178:181], v136 offset:38912
	ds_read_b128 v[182:185], v136 offset:39936
	s_add_u32 s74, s22, 0x100
	s_addc_u32 s75, s23, 0
	s_mov_b32 m0, s29
	s_nop 0
	global_load_lds_dwordx4 v132, s[74:75]
	s_nop 0
	s_mov_b32 m0, s62
	s_nop 0
	global_load_lds_dwordx4 v130, s[74:75]
	s_waitcnt lgkmcnt(8)
	s_barrier
	s_waitcnt lgkmcnt(0)
	s_setprio 1
	v_mfma_f32_16x16x32_bf16 v[126:129], v[138:141], v[154:157], v[126:129]
	v_mfma_f32_16x16x32_bf16 v[126:129], v[142:145], v[158:161], v[126:129]
	v_mfma_f32_16x16x32_bf16 v[122:125], v[146:149], v[154:157], v[122:125]
	v_mfma_f32_16x16x32_bf16 v[122:125], v[150:153], v[158:161], v[122:125]
	v_mfma_f32_16x16x32_bf16 v[118:121], v[138:141], v[162:165], v[118:121]
	v_mfma_f32_16x16x32_bf16 v[118:121], v[142:145], v[166:169], v[118:121]
	v_mfma_f32_16x16x32_bf16 v[114:117], v[146:149], v[162:165], v[114:117]
	v_mfma_f32_16x16x32_bf16 v[114:117], v[150:153], v[166:169], v[114:117]
	v_mfma_f32_16x16x32_bf16 v[110:113], v[138:141], v[170:173], v[110:113]
	v_mfma_f32_16x16x32_bf16 v[110:113], v[142:145], v[174:177], v[110:113]
	v_mfma_f32_16x16x32_bf16 v[106:109], v[146:149], v[170:173], v[106:109]
	v_mfma_f32_16x16x32_bf16 v[106:109], v[150:153], v[174:177], v[106:109]
	v_mfma_f32_16x16x32_bf16 v[102:105], v[138:141], v[178:181], v[102:105]
	v_mfma_f32_16x16x32_bf16 v[102:105], v[142:145], v[182:185], v[102:105]
	v_mfma_f32_16x16x32_bf16 v[98:101], v[146:149], v[178:181], v[98:101]
	v_mfma_f32_16x16x32_bf16 v[98:101], v[150:153], v[182:185], v[98:101]
	s_setprio 0
	s_barrier
	ds_read_b128 v[186:189], v137 offset:49152
	ds_read_b128 v[196:199], v137 offset:50176
	ds_read_b128 v[212:215], v137 offset:51200
	ds_read_b128 v[220:223], v137 offset:52224
	s_add_u32 s74, s49, 0x180
	s_addc_u32 s75, s54, 0
	s_mov_b32 m0, s50
	s_nop 0
	global_load_lds_dwordx4 v132, s[74:75]
	s_nop 0
	s_mov_b32 m0, s51
	s_nop 0
	global_load_lds_dwordx4 v130, s[74:75]
	s_barrier
	s_waitcnt lgkmcnt(0)
	s_setprio 1
	v_mfma_f32_16x16x32_bf16 v[94:97], v[186:189], v[154:157], v[94:97]
	v_mfma_f32_16x16x32_bf16 v[94:97], v[196:199], v[158:161], v[94:97]
	v_mfma_f32_16x16x32_bf16 v[90:93], v[212:215], v[154:157], v[90:93]
	v_mfma_f32_16x16x32_bf16 v[90:93], v[220:223], v[158:161], v[90:93]
	v_mfma_f32_16x16x32_bf16 v[86:89], v[186:189], v[162:165], v[86:89]
	v_mfma_f32_16x16x32_bf16 v[86:89], v[196:199], v[166:169], v[86:89]
	v_mfma_f32_16x16x32_bf16 v[82:85], v[212:215], v[162:165], v[82:85]
	v_mfma_f32_16x16x32_bf16 v[82:85], v[220:223], v[166:169], v[82:85]
	v_mfma_f32_16x16x32_bf16 v[78:81], v[186:189], v[170:173], v[78:81]
	v_mfma_f32_16x16x32_bf16 v[78:81], v[196:199], v[174:177], v[78:81]
	v_mfma_f32_16x16x32_bf16 v[74:77], v[212:215], v[170:173], v[74:77]
	v_mfma_f32_16x16x32_bf16 v[74:77], v[220:223], v[174:177], v[74:77]
	v_mfma_f32_16x16x32_bf16 v[70:73], v[186:189], v[178:181], v[70:73]
	v_mfma_f32_16x16x32_bf16 v[70:73], v[196:199], v[182:185], v[70:73]
	v_mfma_f32_16x16x32_bf16 v[66:69], v[212:215], v[178:181], v[66:69]
	v_mfma_f32_16x16x32_bf16 v[66:69], v[220:223], v[182:185], v[66:69]
	s_setprio 0
	s_barrier
	ds_read_b128 v[154:157], v136 offset:49152
	ds_read_b128 v[158:161], v136 offset:50176
	ds_read_b128 v[162:165], v136 offset:51200
	ds_read_b128 v[166:169], v136 offset:52224
	ds_read_b128 v[170:173], v136 offset:53248
	ds_read_b128 v[174:177], v136 offset:54272
	ds_read_b128 v[178:181], v136 offset:55296
	ds_read_b128 v[182:185], v136 offset:56320
	s_add_u32 s74, s60, 0x180
	s_addc_u32 s75, s68, 0
	s_mov_b32 m0, s63
	s_nop 0
	global_load_lds_dwordx4 v132, s[74:75]
	s_nop 0
	s_mov_b32 m0, s6
	s_nop 0
	global_load_lds_dwordx4 v130, s[74:75]
	s_barrier
; #define WAIT_V(n) asm volatile("s_waitcnt vmcnt(" #n ")" ::: "memory")
; #define WAIT_L(n) asm volatile("s_waitcnt lgkmcnt(" #n ")" ::: "memory")
; #define BAR __builtin_amdgcn_s_barrier()
; #define SCHED __builtin_amdgcn_sched_barrier(0)
; #define STAGE_A(b, h, kt)                                        \
;   do {                                                           \
;     const char* _g = Ab + (h) * halfK + (long)(kt) * 128;        \
;     GLDS2(_g, (unsigned)(((b) * 2 + (h)) * 16384));              \
;   } while (0)
; #define STAGE_B(b, h, kt)                                        \
;   do {                                                           \
;     const char* _g = Bb + (h) * halfK + (long)(kt) * 128;        \
;     GLDS2(_g, (unsigned)(65536 + ((b) * 2 + (h)) * 16384));      \
;   } while (0)
; #define LDA(dst, b, h)                                                                                   \
;   _Pragma("unroll") for (int m = 0; m < 4; ++m) _Pragma("unroll") for (int k = 0; k < 2; ++k) dst[m][k] = \
;       *reinterpret_cast<const bf16x8*>(aRd + ((b) * 2 + (h)) * 16384 + m * 2048 + k * 1024)
; #define LDB(dst, b, h)                                                                                   \
;   _Pragma("unroll") for (int n = 0; n < 2; ++n) _Pragma("unroll") for (int k = 0; k < 2; ++k) dst[n][k] = \
;       *reinterpret_cast<const bf16x8*>(bRd + ((b) * 2 + (h)) * 16384 + n * 2048 + k * 1024)
; template <int EPI> ...
;     ...
;     MMA(1, 0, At, B0);
;     BAR;
;     SCHED;
;     STAGE_B(1, 1, t + 3);
;     WAIT_V(6);
;     BAR;
;     MMA(1, 1, At, B1);
;     BAR;
;   }
;   {
;     LDB(B0, 0, 0);
;     LDA(At, 0, 0);
;     STAGE_A(1, 1, nt - 1);
;     BAR;
;     WAIT_L(0);
;     MMA(0, 0, At, B0);
;     BAR;
;     LDB(B1, 0, 1);
;     BAR;
;     WAIT_L(0);
;     MMA(0, 1, At, B1);
;     BAR;
	s_waitcnt lgkmcnt(0)
	s_setprio 1
	v_mfma_f32_16x16x32_bf16 v[62:65], v[138:141], v[154:157], v[62:65]
	v_mfma_f32_16x16x32_bf16 v[62:65], v[142:145], v[158:161], v[62:65]
	v_mfma_f32_16x16x32_bf16 v[58:61], v[146:149], v[154:157], v[58:61]
	v_mfma_f32_16x16x32_bf16 v[58:61], v[150:153], v[158:161], v[58:61]
	v_mfma_f32_16x16x32_bf16 v[54:57], v[138:141], v[162:165], v[54:57]
	v_mfma_f32_16x16x32_bf16 v[54:57], v[142:145], v[166:169], v[54:57]
	v_mfma_f32_16x16x32_bf16 v[50:53], v[146:149], v[162:165], v[50:53]
	v_mfma_f32_16x16x32_bf16 v[50:53], v[150:153], v[166:169], v[50:53]
	v_mfma_f32_16x16x32_bf16 v[46:49], v[138:141], v[170:173], v[46:49]
	v_mfma_f32_16x16x32_bf16 v[46:49], v[142:145], v[174:177], v[46:49]
	v_mfma_f32_16x16x32_bf16 v[42:45], v[146:149], v[170:173], v[42:45]
	v_mfma_f32_16x16x32_bf16 v[42:45], v[150:153], v[174:177], v[42:45]
	v_mfma_f32_16x16x32_bf16 v[38:41], v[138:141], v[178:181], v[38:41]
	v_mfma_f32_16x16x32_bf16 v[38:41], v[142:145], v[182:185], v[38:41]
	v_mfma_f32_16x16x32_bf16 v[34:37], v[146:149], v[178:181], v[34:37]
	v_mfma_f32_16x16x32_bf16 v[34:37], v[150:153], v[182:185], v[34:37]
	s_setprio 0
	s_barrier
	s_add_u32 s74, s69, 0x180
	s_addc_u32 s75, s76, 0
	s_mov_b32 m0, s9
	s_nop 0
	global_load_lds_dwordx4 v132, s[74:75]
	s_nop 0
	s_mov_b32 m0, s10
	s_nop 0
	global_load_lds_dwordx4 v130, s[74:75]
	s_waitcnt vmcnt(6)
	s_barrier
	s_setprio 1
	v_mfma_f32_16x16x32_bf16 v[30:33], v[186:189], v[154:157], v[30:33]
	v_mfma_f32_16x16x32_bf16 v[30:33], v[196:199], v[158:161], v[30:33]
	v_mfma_f32_16x16x32_bf16 v[26:29], v[212:215], v[154:157], v[26:29]
	v_mfma_f32_16x16x32_bf16 v[26:29], v[220:223], v[158:161], v[26:29]
	v_mfma_f32_16x16x32_bf16 v[22:25], v[186:189], v[162:165], v[22:25]
	v_mfma_f32_16x16x32_bf16 v[22:25], v[196:199], v[166:169], v[22:25]
	v_mfma_f32_16x16x32_bf16 v[18:21], v[212:215], v[162:165], v[18:21]
	v_mfma_f32_16x16x32_bf16 v[18:21], v[220:223], v[166:169], v[18:21]
	v_mfma_f32_16x16x32_bf16 v[14:17], v[186:189], v[170:173], v[14:17]
	v_mfma_f32_16x16x32_bf16 v[14:17], v[196:199], v[174:177], v[14:17]
	v_mfma_f32_16x16x32_bf16 v[10:13], v[212:215], v[170:173], v[10:13]
	v_mfma_f32_16x16x32_bf16 v[10:13], v[220:223], v[174:177], v[10:13]
	v_mfma_f32_16x16x32_bf16 v[6:9], v[186:189], v[178:181], v[6:9]
	v_mfma_f32_16x16x32_bf16 v[6:9], v[196:199], v[182:185], v[6:9]
	v_mfma_f32_16x16x32_bf16 v[2:5], v[212:215], v[178:181], v[2:5]
	v_mfma_f32_16x16x32_bf16 v[2:5], v[220:223], v[182:185], v[2:5]
	s_setprio 0
	s_add_i32 s91, s91, 2
	s_add_u32 s12, s12, 0x100
	s_addc_u32 s13, s13, 0
	s_cmp_lt_u32 s91, 28
	s_barrier
	s_cbranch_scc1 .LBB0_114
	ds_read_b128 v[138:141], v137
	ds_read_b128 v[142:145], v137 offset:1024
	ds_read_b128 v[146:149], v137 offset:2048
	ds_read_b128 v[150:153], v137 offset:3072
	ds_read_b128 v[154:157], v136
	ds_read_b128 v[158:161], v136 offset:1024
	ds_read_b128 v[162:165], v136 offset:2048
	ds_read_b128 v[166:169], v136 offset:3072
	ds_read_b128 v[170:173], v136 offset:4096
	ds_read_b128 v[174:177], v136 offset:5120
	ds_read_b128 v[178:181], v136 offset:6144
	ds_read_b128 v[182:185], v136 offset:7168
	s_add_u32 s6, s96, 0x80f80
	s_addc_u32 s7, s97, 0
	s_mov_b32 m0, s77
	s_nop 0
	global_load_lds_dwordx4 v132, s[6:7]
	s_nop 0
	s_mov_b32 m0, s64
	s_nop 0
	global_load_lds_dwordx4 v130, s[6:7]
	s_barrier
	s_waitcnt lgkmcnt(0)
	s_setprio 1
	v_mfma_f32_16x16x32_bf16 v[126:129], v[138:141], v[154:157], v[126:129]
	v_mfma_f32_16x16x32_bf16 v[126:129], v[142:145], v[158:161], v[126:129]
	v_mfma_f32_16x16x32_bf16 v[122:125], v[146:149], v[154:157], v[122:125]
	v_mfma_f32_16x16x32_bf16 v[122:125], v[150:153], v[158:161], v[122:125]
	v_mfma_f32_16x16x32_bf16 v[118:121], v[138:141], v[162:165], v[118:121]
	v_mfma_f32_16x16x32_bf16 v[118:121], v[142:145], v[166:169], v[118:121]
	v_mfma_f32_16x16x32_bf16 v[114:117], v[146:149], v[162:165], v[114:117]
	v_mfma_f32_16x16x32_bf16 v[114:117], v[150:153], v[166:169], v[114:117]
	v_mfma_f32_16x16x32_bf16 v[110:113], v[138:141], v[170:173], v[110:113]
	v_mfma_f32_16x16x32_bf16 v[110:113], v[142:145], v[174:177], v[110:113]
	v_mfma_f32_16x16x32_bf16 v[106:109], v[146:149], v[170:173], v[106:109]
	v_mfma_f32_16x16x32_bf16 v[106:109], v[150:153], v[174:177], v[106:109]
	v_mfma_f32_16x16x32_bf16 v[102:105], v[138:141], v[178:181], v[102:105]
	v_mfma_f32_16x16x32_bf16 v[102:105], v[142:145], v[182:185], v[102:105]
	v_mfma_f32_16x16x32_bf16 v[98:101], v[146:149], v[178:181], v[98:101]
	v_mfma_f32_16x16x32_bf16 v[98:101], v[150:153], v[182:185], v[98:101]
	s_setprio 0
	s_barrier
	ds_read_b128 v[186:189], v137 offset:16384
	ds_read_b128 v[196:199], v137 offset:17408
	ds_read_b128 v[212:215], v137 offset:18432
	ds_read_b128 v[220:223], v137 offset:19456
	s_barrier
	s_waitcnt lgkmcnt(0)
	s_setprio 1
	v_mfma_f32_16x16x32_bf16 v[94:97], v[186:189], v[154:157], v[94:97]
	v_mfma_f32_16x16x32_bf16 v[94:97], v[196:199], v[158:161], v[94:97]
	v_mfma_f32_16x16x32_bf16 v[90:93], v[212:215], v[154:157], v[90:93]
	v_mfma_f32_16x16x32_bf16 v[90:93], v[220:223], v[158:161], v[90:93]
	v_mfma_f32_16x16x32_bf16 v[86:89], v[186:189], v[162:165], v[86:89]
	v_mfma_f32_16x16x32_bf16 v[86:89], v[196:199], v[166:169], v[86:89]
	v_mfma_f32_16x16x32_bf16 v[82:85], v[212:215], v[162:165], v[82:85]
	v_mfma_f32_16x16x32_bf16 v[82:85], v[220:223], v[166:169], v[82:85]
	v_mfma_f32_16x16x32_bf16 v[78:81], v[186:189], v[170:173], v[78:81]
	v_mfma_f32_16x16x32_bf16 v[78:81], v[196:199], v[174:177], v[78:81]
	v_mfma_f32_16x16x32_bf16 v[74:77], v[212:215], v[170:173], v[74:77]
	v_mfma_f32_16x16x32_bf16 v[74:77], v[220:223], v[174:177], v[74:77]
	v_mfma_f32_16x16x32_bf16 v[70:73], v[186:189], v[178:181], v[70:73]
	v_mfma_f32_16x16x32_bf16 v[70:73], v[196:199], v[182:185], v[70:73]
	v_mfma_f32_16x16x32_bf16 v[66:69], v[212:215], v[178:181], v[66:69]
	v_mfma_f32_16x16x32_bf16 v[66:69], v[220:223], v[182:185], v[66:69]
	s_setprio 0
	s_barrier
; #define WAIT_V(n) asm volatile("s_waitcnt vmcnt(" #n ")" ::: "memory")
; #define WAIT_L(n) asm volatile("s_waitcnt lgkmcnt(" #n ")" ::: "memory")
; #define BAR __builtin_amdgcn_s_barrier()
; #define LDA(dst, b, h)                                                                                   \
;   _Pragma("unroll") for (int m = 0; m < 4; ++m) _Pragma("unroll") for (int k = 0; k < 2; ++k) dst[m][k] = \
;       *reinterpret_cast<const bf16x8*>(aRd + ((b) * 2 + (h)) * 16384 + m * 2048 + k * 1024)
; #define LDB(dst, b, h)                                                                                   \
;   _Pragma("unroll") for (int n = 0; n < 2; ++n) _Pragma("unroll") for (int k = 0; k < 2; ++k) dst[n][k] = \
;       *reinterpret_cast<const bf16x8*>(bRd + ((b) * 2 + (h)) * 16384 + n * 2048 + k * 1024)
; template <int EPI> ...
;     ...
;     LDA(At, 0, 1);
;     WAIT_V(4);
;     BAR;
;     WAIT_L(0);
;     MMA(1, 0, At, B0);
;     MMA(1, 1, At, B1);
;     BAR;
;   }
;   {
;     LDB(B0, 1, 0);
;     LDA(At, 1, 0);
;     WAIT_V(2);
;     BAR;
;     WAIT_L(0);
;     MMA(0, 0, At, B0);
	ds_read_b128 v[154:157], v136 offset:16384
	ds_read_b128 v[158:161], v136 offset:17408
	ds_read_b128 v[162:165], v136 offset:18432
	ds_read_b128 v[166:169], v136 offset:19456
	ds_read_b128 v[170:173], v136 offset:20480
	ds_read_b128 v[174:177], v136 offset:21504
	ds_read_b128 v[178:181], v136 offset:22528
	ds_read_b128 v[182:185], v136 offset:23552
	s_waitcnt vmcnt(4)
	s_barrier
	s_waitcnt lgkmcnt(0)
	s_setprio 1
	v_mfma_f32_16x16x32_bf16 v[62:65], v[138:141], v[154:157], v[62:65]
	v_mfma_f32_16x16x32_bf16 v[62:65], v[142:145], v[158:161], v[62:65]
	v_mfma_f32_16x16x32_bf16 v[58:61], v[146:149], v[154:157], v[58:61]
	v_mfma_f32_16x16x32_bf16 v[58:61], v[150:153], v[158:161], v[58:61]
	v_mfma_f32_16x16x32_bf16 v[54:57], v[138:141], v[162:165], v[54:57]
	v_mfma_f32_16x16x32_bf16 v[54:57], v[142:145], v[166:169], v[54:57]
	v_mfma_f32_16x16x32_bf16 v[50:53], v[146:149], v[162:165], v[50:53]
	v_mfma_f32_16x16x32_bf16 v[50:53], v[150:153], v[166:169], v[50:53]
	v_mfma_f32_16x16x32_bf16 v[46:49], v[138:141], v[170:173], v[46:49]
	v_mfma_f32_16x16x32_bf16 v[46:49], v[142:145], v[174:177], v[46:49]
	v_mfma_f32_16x16x32_bf16 v[42:45], v[146:149], v[170:173], v[42:45]
	v_mfma_f32_16x16x32_bf16 v[42:45], v[150:153], v[174:177], v[42:45]
	v_mfma_f32_16x16x32_bf16 v[38:41], v[138:141], v[178:181], v[38:41]
	v_mfma_f32_16x16x32_bf16 v[38:41], v[142:145], v[182:185], v[38:41]
	v_mfma_f32_16x16x32_bf16 v[34:37], v[146:149], v[178:181], v[34:37]
	v_mfma_f32_16x16x32_bf16 v[34:37], v[150:153], v[182:185], v[34:37]
	s_setprio 0
	s_setprio 1
	v_mfma_f32_16x16x32_bf16 v[30:33], v[186:189], v[154:157], v[30:33]
	v_mfma_f32_16x16x32_bf16 v[30:33], v[196:199], v[158:161], v[30:33]
	v_mfma_f32_16x16x32_bf16 v[26:29], v[212:215], v[154:157], v[26:29]
	v_mfma_f32_16x16x32_bf16 v[26:29], v[220:223], v[158:161], v[26:29]
	v_mfma_f32_16x16x32_bf16 v[22:25], v[186:189], v[162:165], v[22:25]
	v_mfma_f32_16x16x32_bf16 v[22:25], v[196:199], v[166:169], v[22:25]
	v_mfma_f32_16x16x32_bf16 v[18:21], v[212:215], v[162:165], v[18:21]
	v_mfma_f32_16x16x32_bf16 v[18:21], v[220:223], v[166:169], v[18:21]
	v_mfma_f32_16x16x32_bf16 v[14:17], v[186:189], v[170:173], v[14:17]
	v_mfma_f32_16x16x32_bf16 v[14:17], v[196:199], v[174:177], v[14:17]
	v_mfma_f32_16x16x32_bf16 v[10:13], v[212:215], v[170:173], v[10:13]
	v_mfma_f32_16x16x32_bf16 v[10:13], v[220:223], v[174:177], v[10:13]
	v_mfma_f32_16x16x32_bf16 v[6:9], v[186:189], v[178:181], v[6:9]
	v_mfma_f32_16x16x32_bf16 v[6:9], v[196:199], v[182:185], v[6:9]
	v_mfma_f32_16x16x32_bf16 v[2:5], v[212:215], v[178:181], v[2:5]
	v_mfma_f32_16x16x32_bf16 v[2:5], v[220:223], v[182:185], v[2:5]
	s_setprio 0
	s_barrier
	ds_read_b128 v[138:141], v137 offset:32768
	ds_read_b128 v[142:145], v137 offset:33792
	ds_read_b128 v[146:149], v137 offset:34816
	ds_read_b128 v[150:153], v137 offset:35840
	ds_read_b128 v[154:157], v136 offset:32768
	ds_read_b128 v[158:161], v136 offset:33792
	ds_read_b128 v[162:165], v136 offset:34816
	ds_read_b128 v[166:169], v136 offset:35840
	ds_read_b128 v[170:173], v136 offset:36864
	ds_read_b128 v[174:177], v136 offset:37888
	ds_read_b128 v[178:181], v136 offset:38912
	ds_read_b128 v[182:185], v136 offset:39936
	s_waitcnt vmcnt(2)
	s_barrier
	s_waitcnt lgkmcnt(0)
	s_setprio 1
	v_mfma_f32_16x16x32_bf16 v[126:129], v[138:141], v[154:157], v[126:129]
	v_mfma_f32_16x16x32_bf16 v[126:129], v[142:145], v[158:161], v[126:129]
	v_mfma_f32_16x16x32_bf16 v[122:125], v[146:149], v[154:157], v[122:125]
	v_mfma_f32_16x16x32_bf16 v[122:125], v[150:153], v[158:161], v[122:125]
	v_mfma_f32_16x16x32_bf16 v[118:121], v[138:141], v[162:165], v[118:121]
	v_mfma_f32_16x16x32_bf16 v[118:121], v[142:145], v[166:169], v[118:121]
	v_mfma_f32_16x16x32_bf16 v[114:117], v[146:149], v[162:165], v[114:117]
	v_mfma_f32_16x16x32_bf16 v[114:117], v[150:153], v[166:169], v[114:117]
	v_mfma_f32_16x16x32_bf16 v[110:113], v[138:141], v[170:173], v[110:113]
	v_mfma_f32_16x16x32_bf16 v[110:113], v[142:145], v[174:177], v[110:113]
	v_mfma_f32_16x16x32_bf16 v[106:109], v[146:149], v[170:173], v[106:109]
	v_mfma_f32_16x16x32_bf16 v[106:109], v[150:153], v[174:177], v[106:109]
	v_mfma_f32_16x16x32_bf16 v[102:105], v[138:141], v[178:181], v[102:105]
	v_mfma_f32_16x16x32_bf16 v[102:105], v[142:145], v[182:185], v[102:105]
	v_mfma_f32_16x16x32_bf16 v[98:101], v[146:149], v[178:181], v[98:101]
	v_mfma_f32_16x16x32_bf16 v[98:101], v[150:153], v[182:185], v[98:101]
	s_setprio 0
	s_barrier
; #define WAIT_V(n) asm volatile("s_waitcnt vmcnt(" #n ")" ::: "memory")
; #define WAIT_L(n) asm volatile("s_waitcnt lgkmcnt(" #n ")" ::: "memory")
; #define BAR __builtin_amdgcn_s_barrier()
; #define LDA(dst, b, h)                                                                                   \
;   _Pragma("unroll") for (int m = 0; m < 4; ++m) _Pragma("unroll") for (int k = 0; k < 2; ++k) dst[m][k] = \
;       *reinterpret_cast<const bf16x8*>(aRd + ((b) * 2 + (h)) * 16384 + m * 2048 + k * 1024)
; #define LDB(dst, b, h)                                                                                   \
;   _Pragma("unroll") for (int n = 0; n < 2; ++n) _Pragma("unroll") for (int k = 0; k < 2; ++k) dst[n][k] = \
;       *reinterpret_cast<const bf16x8*>(bRd + ((b) * 2 + (h)) * 16384 + n * 2048 + k * 1024)
; template <int EPI> ...
;     ...
;     BAR;
;     LDB(B1, 1, 1);
;     WAIT_V(0);
;     BAR;
;     WAIT_L(0);
;     MMA(0, 1, At, B1);
;     BAR;
;     LDA(At, 1, 1);
;     BAR;
;     WAIT_L(0);
;     MMA(1, 0, At, B0);
;     MMA(1, 1, At, B1);
;     BAR;
;   }
;   if (wr == 0) BAR;
;   if (nAb) {
	ds_read_b128 v[186:189], v137 offset:49152
	ds_read_b128 v[196:199], v137 offset:50176
	ds_read_b128 v[212:215], v137 offset:51200
	ds_read_b128 v[220:223], v137 offset:52224
	s_waitcnt vmcnt(0)
	s_barrier
	s_waitcnt lgkmcnt(0)
	s_setprio 1
	v_mfma_f32_16x16x32_bf16 v[94:97], v[186:189], v[154:157], v[94:97]
	v_mfma_f32_16x16x32_bf16 v[94:97], v[196:199], v[158:161], v[94:97]
	v_mfma_f32_16x16x32_bf16 v[90:93], v[212:215], v[154:157], v[90:93]
	v_mfma_f32_16x16x32_bf16 v[90:93], v[220:223], v[158:161], v[90:93]
	v_mfma_f32_16x16x32_bf16 v[86:89], v[186:189], v[162:165], v[86:89]
	v_mfma_f32_16x16x32_bf16 v[86:89], v[196:199], v[166:169], v[86:89]
	v_mfma_f32_16x16x32_bf16 v[82:85], v[212:215], v[162:165], v[82:85]
	v_mfma_f32_16x16x32_bf16 v[82:85], v[220:223], v[166:169], v[82:85]
	v_mfma_f32_16x16x32_bf16 v[78:81], v[186:189], v[170:173], v[78:81]
	v_mfma_f32_16x16x32_bf16 v[78:81], v[196:199], v[174:177], v[78:81]
	v_mfma_f32_16x16x32_bf16 v[74:77], v[212:215], v[170:173], v[74:77]
	v_mfma_f32_16x16x32_bf16 v[74:77], v[220:223], v[174:177], v[74:77]
	v_mfma_f32_16x16x32_bf16 v[70:73], v[186:189], v[178:181], v[70:73]
	v_mfma_f32_16x16x32_bf16 v[70:73], v[196:199], v[182:185], v[70:73]
	v_mfma_f32_16x16x32_bf16 v[66:69], v[212:215], v[178:181], v[66:69]
	v_mfma_f32_16x16x32_bf16 v[66:69], v[220:223], v[182:185], v[66:69]
	s_setprio 0
	s_barrier
	ds_read_b128 v[154:157], v136 offset:49152
	ds_read_b128 v[158:161], v136 offset:50176
	ds_read_b128 v[162:165], v136 offset:51200
	ds_read_b128 v[166:169], v136 offset:52224
	ds_read_b128 v[170:173], v136 offset:53248
	ds_read_b128 v[174:177], v136 offset:54272
	ds_read_b128 v[178:181], v136 offset:55296
	ds_read_b128 v[182:185], v136 offset:56320
	s_barrier
	s_waitcnt lgkmcnt(0)
	s_setprio 1
	v_mfma_f32_16x16x32_bf16 v[62:65], v[138:141], v[154:157], v[62:65]
	v_mfma_f32_16x16x32_bf16 v[62:65], v[142:145], v[158:161], v[62:65]
	v_mfma_f32_16x16x32_bf16 v[58:61], v[146:149], v[154:157], v[58:61]
	v_mfma_f32_16x16x32_bf16 v[58:61], v[150:153], v[158:161], v[58:61]
	v_mfma_f32_16x16x32_bf16 v[54:57], v[138:141], v[162:165], v[54:57]
	v_mfma_f32_16x16x32_bf16 v[54:57], v[142:145], v[166:169], v[54:57]
	v_mfma_f32_16x16x32_bf16 v[50:53], v[146:149], v[162:165], v[50:53]
	v_mfma_f32_16x16x32_bf16 v[50:53], v[150:153], v[166:169], v[50:53]
	v_mfma_f32_16x16x32_bf16 v[46:49], v[138:141], v[170:173], v[46:49]
	v_mfma_f32_16x16x32_bf16 v[46:49], v[142:145], v[174:177], v[46:49]
	v_mfma_f32_16x16x32_bf16 v[42:45], v[146:149], v[170:173], v[42:45]
	v_mfma_f32_16x16x32_bf16 v[42:45], v[150:153], v[174:177], v[42:45]
	v_mfma_f32_16x16x32_bf16 v[38:41], v[138:141], v[178:181], v[38:41]
	v_mfma_f32_16x16x32_bf16 v[38:41], v[142:145], v[182:185], v[38:41]
	v_mfma_f32_16x16x32_bf16 v[34:37], v[146:149], v[178:181], v[34:37]
	v_mfma_f32_16x16x32_bf16 v[34:37], v[150:153], v[182:185], v[34:37]
	s_setprio 0
	s_setprio 1
	v_mfma_f32_16x16x32_bf16 v[30:33], v[186:189], v[154:157], v[30:33]
	v_mfma_f32_16x16x32_bf16 v[30:33], v[196:199], v[158:161], v[30:33]
	v_mfma_f32_16x16x32_bf16 v[26:29], v[212:215], v[154:157], v[26:29]
	v_mfma_f32_16x16x32_bf16 v[26:29], v[220:223], v[158:161], v[26:29]
	v_mfma_f32_16x16x32_bf16 v[22:25], v[186:189], v[162:165], v[22:25]
	v_mfma_f32_16x16x32_bf16 v[22:25], v[196:199], v[166:169], v[22:25]
	v_mfma_f32_16x16x32_bf16 v[18:21], v[212:215], v[162:165], v[18:21]
	v_mfma_f32_16x16x32_bf16 v[18:21], v[220:223], v[166:169], v[18:21]
	v_mfma_f32_16x16x32_bf16 v[14:17], v[186:189], v[170:173], v[14:17]
	v_mfma_f32_16x16x32_bf16 v[14:17], v[196:199], v[174:177], v[14:17]
	v_mfma_f32_16x16x32_bf16 v[10:13], v[212:215], v[170:173], v[10:13]
	v_mfma_f32_16x16x32_bf16 v[10:13], v[220:223], v[174:177], v[10:13]
	v_mfma_f32_16x16x32_bf16 v[6:9], v[186:189], v[178:181], v[6:9]
	v_mfma_f32_16x16x32_bf16 v[6:9], v[196:199], v[182:185], v[6:9]
	v_mfma_f32_16x16x32_bf16 v[2:5], v[212:215], v[178:181], v[2:5]
	v_mfma_f32_16x16x32_bf16 v[2:5], v[220:223], v[182:185], v[2:5]
	s_setprio 0
	s_movk_i32 s6, 0x100
	v_cmp_gt_u32_e32 vcc, s6, v134
	s_barrier
	s_and_saveexec_b64 s[12:13], vcc
	s_cbranch_execz .LBB0_117
	s_barrier

; #define WAIT_V(n) asm volatile("s_waitcnt vmcnt(" #n ")" ::: "memory")
; #define WAIT_L(n) asm volatile("s_waitcnt lgkmcnt(" #n ")" ::: "memory")
; #define BAR __builtin_amdgcn_s_barrier()
; #define SCHED __builtin_amdgcn_sched_barrier(0)
; #define STAGE_A(b, h, kt)                                        \
;   do {                                                           \
;     const char* _g = Ab + (h) * halfK + (long)(kt) * 128;        \
;     GLDS2(_g, (unsigned)(((b) * 2 + (h)) * 16384));              \
;   } while (0)
; #define STAGE_B(b, h, kt)                                        \
;   do {                                                           \
;     const char* _g = Bb + (h) * halfK + (long)(kt) * 128;        \
;     GLDS2(_g, (unsigned)(65536 + ((b) * 2 + (h)) * 16384));      \
;   } while (0)
; #define LDA(dst, b, h)                                                                                   \
;   _Pragma("unroll") for (int m = 0; m < 4; ++m) _Pragma("unroll") for (int k = 0; k < 2; ++k) dst[m][k] = \
;       *reinterpret_cast<const bf16x8*>(aRd + ((b) * 2 + (h)) * 16384 + m * 2048 + k * 1024)
; #define LDB(dst, b, h)                                                                                   \
;   _Pragma("unroll") for (int n = 0; n < 2; ++n) _Pragma("unroll") for (int k = 0; k < 2; ++k) dst[n][k] = \
;       *reinterpret_cast<const bf16x8*>(bRd + ((b) * 2 + (h)) * 16384 + n * 2048 + k * 1024)
; template <int EPI> ...
;     ...
;     LDB(B0, 0, 0);
;     SCHED;
;     LDA(At, 0, 0);
;     STAGE_A(1, 1, t + 1);
;     WAIT_L(8);
;     BAR;
;     WAIT_L(0);
;     MMA(0, 0, At, B0);
;     BAR;
;     SCHED;
;     LDB(B1, 0, 1);
;     STAGE_B(0, 0, t + 2);
;     BAR;
;     WAIT_L(0);
;     MMA(0, 1, At, B1);
;     BAR;
;     LDA(At, 0, 1);
;     STAGE_A(0, 0, t + 2);
;     BAR;
;     WAIT_L(0);
;     MMA(1, 0, At, B0);
;     BAR;
;     SCHED;
;     STAGE_B(0, 1, t + 2);
;     WAIT_V(6);
;     BAR;
;     MMA(1, 1, At, B1);
.LBB0_203:
	ds_read_b128 v[138:141], v137
	ds_read_b128 v[142:145], v137 offset:1024
	ds_read_b128 v[146:149], v137 offset:2048
	ds_read_b128 v[150:153], v137 offset:3072
	ds_read_b128 v[154:157], v136
	ds_read_b128 v[158:161], v136 offset:1024
	ds_read_b128 v[162:165], v136 offset:2048
	ds_read_b128 v[166:169], v136 offset:3072
	ds_read_b128 v[170:173], v136 offset:4096
	ds_read_b128 v[174:177], v136 offset:5120
	ds_read_b128 v[178:181], v136 offset:6144
	ds_read_b128 v[182:185], v136 offset:7168
	s_add_u32 s76, s6, s12
	s_addc_u32 s60, s7, s13
	s_add_u32 s74, s76, 0x80
	s_addc_u32 s75, s60, 0
	s_mov_b32 m0, vcc_lo
	s_nop 0
	global_load_lds_dwordx4 v132, s[74:75]
	s_nop 0
	s_mov_b32 m0, s92
	s_nop 0
	global_load_lds_dwordx4 v131, s[74:75]
	s_waitcnt lgkmcnt(8)
	s_barrier
	s_waitcnt lgkmcnt(0)
	s_setprio 1
	v_mfma_f32_16x16x32_bf16 v[126:129], v[138:141], v[154:157], v[126:129]
	v_mfma_f32_16x16x32_bf16 v[126:129], v[142:145], v[158:161], v[126:129]
	v_mfma_f32_16x16x32_bf16 v[122:125], v[146:149], v[154:157], v[122:125]
	v_mfma_f32_16x16x32_bf16 v[122:125], v[150:153], v[158:161], v[122:125]
	v_mfma_f32_16x16x32_bf16 v[118:121], v[138:141], v[162:165], v[118:121]
	v_mfma_f32_16x16x32_bf16 v[118:121], v[142:145], v[166:169], v[118:121]
	v_mfma_f32_16x16x32_bf16 v[114:117], v[146:149], v[162:165], v[114:117]
	v_mfma_f32_16x16x32_bf16 v[114:117], v[150:153], v[166:169], v[114:117]
	v_mfma_f32_16x16x32_bf16 v[110:113], v[138:141], v[170:173], v[110:113]
	v_mfma_f32_16x16x32_bf16 v[110:113], v[142:145], v[174:177], v[110:113]
	v_mfma_f32_16x16x32_bf16 v[106:109], v[146:149], v[170:173], v[106:109]
	v_mfma_f32_16x16x32_bf16 v[106:109], v[150:153], v[174:177], v[106:109]
	v_mfma_f32_16x16x32_bf16 v[102:105], v[138:141], v[178:181], v[102:105]
	v_mfma_f32_16x16x32_bf16 v[102:105], v[142:145], v[182:185], v[102:105]
	v_mfma_f32_16x16x32_bf16 v[98:101], v[146:149], v[178:181], v[98:101]
	v_mfma_f32_16x16x32_bf16 v[98:101], v[150:153], v[182:185], v[98:101]
	s_setprio 0
	s_barrier
	s_add_i32 s34, s34, 2
	ds_read_b128 v[186:189], v137 offset:16384
	ds_read_b128 v[220:223], v137 offset:17408
	ds_read_b128 v[224:227], v137 offset:18432
	ds_read_b128 v[228:231], v137 offset:19456
	s_add_u32 s49, s88, s12
	s_addc_u32 s22, s89, s13
	s_add_u32 s74, s49, 0x100
	s_addc_u32 s75, s22, 0
	s_mov_b32 m0, s20
	s_nop 0
	global_load_lds_dwordx4 v132, s[74:75]
	s_nop 0
	s_mov_b32 m0, s21
	s_nop 0
	global_load_lds_dwordx4 v131, s[74:75]
	s_barrier
	s_waitcnt lgkmcnt(0)
	s_setprio 1
	v_mfma_f32_16x16x32_bf16 v[94:97], v[186:189], v[154:157], v[94:97]
	v_mfma_f32_16x16x32_bf16 v[94:97], v[220:223], v[158:161], v[94:97]
	v_mfma_f32_16x16x32_bf16 v[90:93], v[224:227], v[154:157], v[90:93]
	v_mfma_f32_16x16x32_bf16 v[90:93], v[228:231], v[158:161], v[90:93]
	v_mfma_f32_16x16x32_bf16 v[86:89], v[186:189], v[162:165], v[86:89]
	v_mfma_f32_16x16x32_bf16 v[86:89], v[220:223], v[166:169], v[86:89]
	v_mfma_f32_16x16x32_bf16 v[82:85], v[224:227], v[162:165], v[82:85]
	v_mfma_f32_16x16x32_bf16 v[82:85], v[228:231], v[166:169], v[82:85]
	v_mfma_f32_16x16x32_bf16 v[78:81], v[186:189], v[170:173], v[78:81]
	v_mfma_f32_16x16x32_bf16 v[78:81], v[220:223], v[174:177], v[78:81]
	v_mfma_f32_16x16x32_bf16 v[74:77], v[224:227], v[170:173], v[74:77]
	v_mfma_f32_16x16x32_bf16 v[74:77], v[228:231], v[174:177], v[74:77]
	v_mfma_f32_16x16x32_bf16 v[70:73], v[186:189], v[178:181], v[70:73]
	v_mfma_f32_16x16x32_bf16 v[70:73], v[220:223], v[182:185], v[70:73]
	v_mfma_f32_16x16x32_bf16 v[66:69], v[224:227], v[178:181], v[66:69]
	v_mfma_f32_16x16x32_bf16 v[66:69], v[228:231], v[182:185], v[66:69]
	s_setprio 0
	s_barrier
	ds_read_b128 v[154:157], v136 offset:16384
	ds_read_b128 v[158:161], v136 offset:17408
	ds_read_b128 v[162:165], v136 offset:18432
	ds_read_b128 v[166:169], v136 offset:19456
	ds_read_b128 v[170:173], v136 offset:20480
	ds_read_b128 v[174:177], v136 offset:21504
	ds_read_b128 v[178:181], v136 offset:22528
	ds_read_b128 v[182:185], v136 offset:23552
	s_add_u32 s23, s90, s12
	s_addc_u32 s68, s91, s13
	s_add_u32 s74, s23, 0x100
	s_addc_u32 s75, s68, 0
	s_mov_b32 m0, s63
	s_nop 0
	global_load_lds_dwordx4 v132, s[74:75]
	s_nop 0
	s_mov_b32 m0, s78
	s_nop 0
	global_load_lds_dwordx4 v131, s[74:75]
	s_barrier
	s_waitcnt lgkmcnt(0)
	s_setprio 1
	v_mfma_f32_16x16x32_bf16 v[62:65], v[138:141], v[154:157], v[62:65]
	v_mfma_f32_16x16x32_bf16 v[62:65], v[142:145], v[158:161], v[62:65]
	v_mfma_f32_16x16x32_bf16 v[58:61], v[146:149], v[154:157], v[58:61]
	v_mfma_f32_16x16x32_bf16 v[58:61], v[150:153], v[158:161], v[58:61]
	v_mfma_f32_16x16x32_bf16 v[54:57], v[138:141], v[162:165], v[54:57]
	v_mfma_f32_16x16x32_bf16 v[54:57], v[142:145], v[166:169], v[54:57]
	v_mfma_f32_16x16x32_bf16 v[50:53], v[146:149], v[162:165], v[50:53]
	v_mfma_f32_16x16x32_bf16 v[50:53], v[150:153], v[166:169], v[50:53]
	v_mfma_f32_16x16x32_bf16 v[46:49], v[138:141], v[170:173], v[46:49]
	v_mfma_f32_16x16x32_bf16 v[46:49], v[142:145], v[174:177], v[46:49]
	v_mfma_f32_16x16x32_bf16 v[42:45], v[146:149], v[170:173], v[42:45]
	v_mfma_f32_16x16x32_bf16 v[42:45], v[150:153], v[174:177], v[42:45]
	v_mfma_f32_16x16x32_bf16 v[38:41], v[138:141], v[178:181], v[38:41]
	v_mfma_f32_16x16x32_bf16 v[38:41], v[142:145], v[182:185], v[38:41]
	v_mfma_f32_16x16x32_bf16 v[34:37], v[146:149], v[178:181], v[34:37]
	v_mfma_f32_16x16x32_bf16 v[34:37], v[150:153], v[182:185], v[34:37]
	s_setprio 0
	s_barrier
	s_add_u32 s69, s8, s12
	s_addc_u32 s54, s9, s13
	s_add_u32 s74, s69, 0x100
	s_addc_u32 s75, s54, 0
	s_mov_b32 m0, s79
	s_nop 0
	global_load_lds_dwordx4 v132, s[74:75]
	s_nop 0
	s_mov_b32 m0, s38
	s_nop 0
	global_load_lds_dwordx4 v131, s[74:75]
	s_waitcnt vmcnt(6)
	s_barrier
; #define WAIT_L(n) asm volatile("s_waitcnt lgkmcnt(" #n ")" ::: "memory")
; #define BAR __builtin_amdgcn_s_barrier()
; #define SCHED __builtin_amdgcn_sched_barrier(0)
; #define STAGE_A(b, h, kt)                                        \
;   do {                                                           \
;     const char* _g = Ab + (h) * halfK + (long)(kt) * 128;        \
;     GLDS2(_g, (unsigned)(((b) * 2 + (h)) * 16384));              \
;   } while (0)
; #define STAGE_B(b, h, kt)                                        \
;   do {                                                           \
;     const char* _g = Bb + (h) * halfK + (long)(kt) * 128;        \
;     GLDS2(_g, (unsigned)(65536 + ((b) * 2 + (h)) * 16384));      \
;   } while (0)
; #define LDA(dst, b, h)                                                                                   \
;   _Pragma("unroll") for (int m = 0; m < 4; ++m) _Pragma("unroll") for (int k = 0; k < 2; ++k) dst[m][k] = \
;       *reinterpret_cast<const bf16x8*>(aRd + ((b) * 2 + (h)) * 16384 + m * 2048 + k * 1024)
; #define LDB(dst, b, h)                                                                                   \
;   _Pragma("unroll") for (int n = 0; n < 2; ++n) _Pragma("unroll") for (int k = 0; k < 2; ++k) dst[n][k] = \
;       *reinterpret_cast<const bf16x8*>(bRd + ((b) * 2 + (h)) * 16384 + n * 2048 + k * 1024)
; template <int EPI> ...
;     ...
;     MMA(1, 1, At, B1);
;     BAR;
;     LDB(B0, 1, 0);
;     SCHED;
;     LDA(At, 1, 0);
;     STAGE_A(0, 1, t + 2);
;     WAIT_L(8);
;     BAR;
;     WAIT_L(0);
;     MMA(0, 0, At, B0);
;     BAR;
;     SCHED;
;     LDB(B1, 1, 1);
;     STAGE_B(1, 0, t + 3);
;     BAR;
;     WAIT_L(0);
;     MMA(0, 1, At, B1);
;     BAR;
;     LDA(At, 1, 1);
;     STAGE_A(1, 0, t + 3);
;     BAR;
;     WAIT_L(0);
;     MMA(1, 0, At, B0);
;     BAR;
;     SCHED;
;     STAGE_B(1, 1, t + 3);
	s_setprio 1
	v_mfma_f32_16x16x32_bf16 v[30:33], v[186:189], v[154:157], v[30:33]
	v_mfma_f32_16x16x32_bf16 v[30:33], v[220:223], v[158:161], v[30:33]
	v_mfma_f32_16x16x32_bf16 v[26:29], v[224:227], v[154:157], v[26:29]
	v_mfma_f32_16x16x32_bf16 v[26:29], v[228:231], v[158:161], v[26:29]
	v_mfma_f32_16x16x32_bf16 v[22:25], v[186:189], v[162:165], v[22:25]
	v_mfma_f32_16x16x32_bf16 v[22:25], v[220:223], v[166:169], v[22:25]
	v_mfma_f32_16x16x32_bf16 v[18:21], v[224:227], v[162:165], v[18:21]
	v_mfma_f32_16x16x32_bf16 v[18:21], v[228:231], v[166:169], v[18:21]
	v_mfma_f32_16x16x32_bf16 v[14:17], v[186:189], v[170:173], v[14:17]
	v_mfma_f32_16x16x32_bf16 v[14:17], v[220:223], v[174:177], v[14:17]
	v_mfma_f32_16x16x32_bf16 v[10:13], v[224:227], v[170:173], v[10:13]
	v_mfma_f32_16x16x32_bf16 v[10:13], v[228:231], v[174:177], v[10:13]
	v_mfma_f32_16x16x32_bf16 v[6:9], v[186:189], v[178:181], v[6:9]
	v_mfma_f32_16x16x32_bf16 v[6:9], v[220:223], v[182:185], v[6:9]
	v_mfma_f32_16x16x32_bf16 v[2:5], v[224:227], v[178:181], v[2:5]
	v_mfma_f32_16x16x32_bf16 v[2:5], v[228:231], v[182:185], v[2:5]
	s_setprio 0
	s_barrier
	ds_read_b128 v[138:141], v137 offset:32768
	ds_read_b128 v[142:145], v137 offset:33792
	ds_read_b128 v[146:149], v137 offset:34816
	ds_read_b128 v[150:153], v137 offset:35840
	ds_read_b128 v[154:157], v136 offset:32768
	ds_read_b128 v[158:161], v136 offset:33792
	ds_read_b128 v[162:165], v136 offset:34816
	ds_read_b128 v[166:169], v136 offset:35840
	ds_read_b128 v[170:173], v136 offset:36864
	ds_read_b128 v[174:177], v136 offset:37888
	ds_read_b128 v[178:181], v136 offset:38912
	ds_read_b128 v[182:185], v136 offset:39936
	s_add_u32 s74, s76, 0x100
	s_addc_u32 s75, s60, 0
	s_mov_b32 m0, s39
	s_nop 0
	global_load_lds_dwordx4 v132, s[74:75]
	s_nop 0
	s_mov_b32 m0, s28
	s_nop 0
	global_load_lds_dwordx4 v131, s[74:75]
	s_waitcnt lgkmcnt(8)
	s_barrier
	s_waitcnt lgkmcnt(0)
	s_setprio 1
	v_mfma_f32_16x16x32_bf16 v[126:129], v[138:141], v[154:157], v[126:129]
	v_mfma_f32_16x16x32_bf16 v[126:129], v[142:145], v[158:161], v[126:129]
	v_mfma_f32_16x16x32_bf16 v[122:125], v[146:149], v[154:157], v[122:125]
	v_mfma_f32_16x16x32_bf16 v[122:125], v[150:153], v[158:161], v[122:125]
	v_mfma_f32_16x16x32_bf16 v[118:121], v[138:141], v[162:165], v[118:121]
	v_mfma_f32_16x16x32_bf16 v[118:121], v[142:145], v[166:169], v[118:121]
	v_mfma_f32_16x16x32_bf16 v[114:117], v[146:149], v[162:165], v[114:117]
	v_mfma_f32_16x16x32_bf16 v[114:117], v[150:153], v[166:169], v[114:117]
	v_mfma_f32_16x16x32_bf16 v[110:113], v[138:141], v[170:173], v[110:113]
	v_mfma_f32_16x16x32_bf16 v[110:113], v[142:145], v[174:177], v[110:113]
	v_mfma_f32_16x16x32_bf16 v[106:109], v[146:149], v[170:173], v[106:109]
	v_mfma_f32_16x16x32_bf16 v[106:109], v[150:153], v[174:177], v[106:109]
	v_mfma_f32_16x16x32_bf16 v[102:105], v[138:141], v[178:181], v[102:105]
	v_mfma_f32_16x16x32_bf16 v[102:105], v[142:145], v[182:185], v[102:105]
	v_mfma_f32_16x16x32_bf16 v[98:101], v[146:149], v[178:181], v[98:101]
	v_mfma_f32_16x16x32_bf16 v[98:101], v[150:153], v[182:185], v[98:101]
	s_setprio 0
	s_barrier
	ds_read_b128 v[186:189], v137 offset:49152
	ds_read_b128 v[220:223], v137 offset:50176
	ds_read_b128 v[224:227], v137 offset:51200
	ds_read_b128 v[228:231], v137 offset:52224
	s_add_u32 s74, s49, 0x180
	s_addc_u32 s75, s22, 0
	s_mov_b32 m0, s50
	s_nop 0
	global_load_lds_dwordx4 v132, s[74:75]
	s_nop 0
	s_mov_b32 m0, s51
	s_nop 0
	global_load_lds_dwordx4 v131, s[74:75]
	s_barrier
	s_waitcnt lgkmcnt(0)
	s_setprio 1
	v_mfma_f32_16x16x32_bf16 v[94:97], v[186:189], v[154:157], v[94:97]
	v_mfma_f32_16x16x32_bf16 v[94:97], v[220:223], v[158:161], v[94:97]
	v_mfma_f32_16x16x32_bf16 v[90:93], v[224:227], v[154:157], v[90:93]
	v_mfma_f32_16x16x32_bf16 v[90:93], v[228:231], v[158:161], v[90:93]
	v_mfma_f32_16x16x32_bf16 v[86:89], v[186:189], v[162:165], v[86:89]
	v_mfma_f32_16x16x32_bf16 v[86:89], v[220:223], v[166:169], v[86:89]
	v_mfma_f32_16x16x32_bf16 v[82:85], v[224:227], v[162:165], v[82:85]
	v_mfma_f32_16x16x32_bf16 v[82:85], v[228:231], v[166:169], v[82:85]
	v_mfma_f32_16x16x32_bf16 v[78:81], v[186:189], v[170:173], v[78:81]
	v_mfma_f32_16x16x32_bf16 v[78:81], v[220:223], v[174:177], v[78:81]
	v_mfma_f32_16x16x32_bf16 v[74:77], v[224:227], v[170:173], v[74:77]
	v_mfma_f32_16x16x32_bf16 v[74:77], v[228:231], v[174:177], v[74:77]
	v_mfma_f32_16x16x32_bf16 v[70:73], v[186:189], v[178:181], v[70:73]
	v_mfma_f32_16x16x32_bf16 v[70:73], v[220:223], v[182:185], v[70:73]
	v_mfma_f32_16x16x32_bf16 v[66:69], v[224:227], v[178:181], v[66:69]
	v_mfma_f32_16x16x32_bf16 v[66:69], v[228:231], v[182:185], v[66:69]
	s_setprio 0
	s_barrier
	ds_read_b128 v[154:157], v136 offset:49152
	ds_read_b128 v[158:161], v136 offset:50176
	ds_read_b128 v[162:165], v136 offset:51200
	ds_read_b128 v[166:169], v136 offset:52224
	ds_read_b128 v[170:173], v136 offset:53248
	ds_read_b128 v[174:177], v136 offset:54272
	ds_read_b128 v[178:181], v136 offset:55296
	ds_read_b128 v[182:185], v136 offset:56320
	s_add_u32 s74, s23, 0x180
	s_addc_u32 s75, s68, 0
	s_mov_b32 m0, s93
	s_nop 0
	global_load_lds_dwordx4 v132, s[74:75]
	s_nop 0
	s_mov_b32 m0, vcc_hi
	s_nop 0
	global_load_lds_dwordx4 v131, s[74:75]
	s_barrier
; #define WAIT_V(n) asm volatile("s_waitcnt vmcnt(" #n ")" ::: "memory")
; #define WAIT_L(n) asm volatile("s_waitcnt lgkmcnt(" #n ")" ::: "memory")
; #define BAR __builtin_amdgcn_s_barrier()
; #define SCHED __builtin_amdgcn_sched_barrier(0)
; #define STAGE_A(b, h, kt)                                        \
;   do {                                                           \
;     const char* _g = Ab + (h) * halfK + (long)(kt) * 128;        \
;     GLDS2(_g, (unsigned)(((b) * 2 + (h)) * 16384));              \
;   } while (0)
; #define STAGE_B(b, h, kt)                                        \
;   do {                                                           \
;     const char* _g = Bb + (h) * halfK + (long)(kt) * 128;        \
;     GLDS2(_g, (unsigned)(65536 + ((b) * 2 + (h)) * 16384));      \
;   } while (0)
; #define LDA(dst, b, h)                                                                                   \
;   _Pragma("unroll") for (int m = 0; m < 4; ++m) _Pragma("unroll") for (int k = 0; k < 2; ++k) dst[m][k] = \
;       *reinterpret_cast<const bf16x8*>(aRd + ((b) * 2 + (h)) * 16384 + m * 2048 + k * 1024)
; #define LDB(dst, b, h)                                                                                   \
;   _Pragma("unroll") for (int n = 0; n < 2; ++n) _Pragma("unroll") for (int k = 0; k < 2; ++k) dst[n][k] = \
;       *reinterpret_cast<const bf16x8*>(bRd + ((b) * 2 + (h)) * 16384 + n * 2048 + k * 1024)
; template <int EPI> ...
;     ...
;     MMA(1, 0, At, B0);
;     BAR;
;     SCHED;
;     STAGE_B(1, 1, t + 3);
;     WAIT_V(6);
;     BAR;
;     MMA(1, 1, At, B1);
;     BAR;
;   }
;   {
;     LDB(B0, 0, 0);
;     LDA(At, 0, 0);
;     STAGE_A(1, 1, nt - 1);
;     BAR;
;     WAIT_L(0);
;     MMA(0, 0, At, B0);
;     BAR;
;     LDB(B1, 0, 1);
;     BAR;
;     WAIT_L(0);
;     MMA(0, 1, At, B1);
;     BAR;
	s_waitcnt lgkmcnt(0)
	s_setprio 1
	v_mfma_f32_16x16x32_bf16 v[62:65], v[138:141], v[154:157], v[62:65]
	v_mfma_f32_16x16x32_bf16 v[62:65], v[142:145], v[158:161], v[62:65]
	v_mfma_f32_16x16x32_bf16 v[58:61], v[146:149], v[154:157], v[58:61]
	v_mfma_f32_16x16x32_bf16 v[58:61], v[150:153], v[158:161], v[58:61]
	v_mfma_f32_16x16x32_bf16 v[54:57], v[138:141], v[162:165], v[54:57]
	v_mfma_f32_16x16x32_bf16 v[54:57], v[142:145], v[166:169], v[54:57]
	v_mfma_f32_16x16x32_bf16 v[50:53], v[146:149], v[162:165], v[50:53]
	v_mfma_f32_16x16x32_bf16 v[50:53], v[150:153], v[166:169], v[50:53]
	v_mfma_f32_16x16x32_bf16 v[46:49], v[138:141], v[170:173], v[46:49]
	v_mfma_f32_16x16x32_bf16 v[46:49], v[142:145], v[174:177], v[46:49]
	v_mfma_f32_16x16x32_bf16 v[42:45], v[146:149], v[170:173], v[42:45]
	v_mfma_f32_16x16x32_bf16 v[42:45], v[150:153], v[174:177], v[42:45]
	v_mfma_f32_16x16x32_bf16 v[38:41], v[138:141], v[178:181], v[38:41]
	v_mfma_f32_16x16x32_bf16 v[38:41], v[142:145], v[182:185], v[38:41]
	v_mfma_f32_16x16x32_bf16 v[34:37], v[146:149], v[178:181], v[34:37]
	v_mfma_f32_16x16x32_bf16 v[34:37], v[150:153], v[182:185], v[34:37]
	s_setprio 0
	s_barrier
	s_add_u32 s74, s69, 0x180
	s_addc_u32 s75, s54, 0
	s_mov_b32 m0, s10
	s_nop 0
	global_load_lds_dwordx4 v132, s[74:75]
	s_nop 0
	s_mov_b32 m0, s11
	s_nop 0
	global_load_lds_dwordx4 v131, s[74:75]
	s_waitcnt vmcnt(6)
	s_barrier
	s_setprio 1
	v_mfma_f32_16x16x32_bf16 v[30:33], v[186:189], v[154:157], v[30:33]
	v_mfma_f32_16x16x32_bf16 v[30:33], v[220:223], v[158:161], v[30:33]
	v_mfma_f32_16x16x32_bf16 v[26:29], v[224:227], v[154:157], v[26:29]
	v_mfma_f32_16x16x32_bf16 v[26:29], v[228:231], v[158:161], v[26:29]
	v_mfma_f32_16x16x32_bf16 v[22:25], v[186:189], v[162:165], v[22:25]
	v_mfma_f32_16x16x32_bf16 v[22:25], v[220:223], v[166:169], v[22:25]
	v_mfma_f32_16x16x32_bf16 v[18:21], v[224:227], v[162:165], v[18:21]
	v_mfma_f32_16x16x32_bf16 v[18:21], v[228:231], v[166:169], v[18:21]
	v_mfma_f32_16x16x32_bf16 v[14:17], v[186:189], v[170:173], v[14:17]
	v_mfma_f32_16x16x32_bf16 v[14:17], v[220:223], v[174:177], v[14:17]
	v_mfma_f32_16x16x32_bf16 v[10:13], v[224:227], v[170:173], v[10:13]
	v_mfma_f32_16x16x32_bf16 v[10:13], v[228:231], v[174:177], v[10:13]
	v_mfma_f32_16x16x32_bf16 v[6:9], v[186:189], v[178:181], v[6:9]
	v_mfma_f32_16x16x32_bf16 v[6:9], v[220:223], v[182:185], v[6:9]
	v_mfma_f32_16x16x32_bf16 v[2:5], v[224:227], v[178:181], v[2:5]
	v_mfma_f32_16x16x32_bf16 v[2:5], v[228:231], v[182:185], v[2:5]
	s_setprio 0
	s_add_u32 s12, s12, 0x100
	s_addc_u32 s13, s13, 0
	s_cmp_lt_i32 s34, s29
	s_barrier
	s_cbranch_scc1 .LBB0_203
	ds_read_b128 v[138:141], v137
	ds_read_b128 v[142:145], v137 offset:1024
	ds_read_b128 v[146:149], v137 offset:2048
	ds_read_b128 v[150:153], v137 offset:3072
	ds_read_b128 v[154:157], v136
	ds_read_b128 v[158:161], v136 offset:1024
	ds_read_b128 v[162:165], v136 offset:2048
	ds_read_b128 v[166:169], v136 offset:3072
	ds_read_b128 v[170:173], v136 offset:4096
	ds_read_b128 v[174:177], v136 offset:5120
	ds_read_b128 v[178:181], v136 offset:6144
	ds_read_b128 v[182:185], v136 offset:7168
	s_add_i32 s34, s37, -1
	s_lshl_b64 s[8:9], s[34:35], 7
	s_add_u32 s6, s6, s8
	s_addc_u32 s7, s7, s9
	s_mov_b32 m0, vcc_lo
	s_nop 0
	global_load_lds_dwordx4 v132, s[6:7]
	s_nop 0
	s_mov_b32 m0, s92
	s_nop 0
	global_load_lds_dwordx4 v131, s[6:7]
	s_barrier
	s_waitcnt lgkmcnt(0)
	s_setprio 1
	s_waitcnt lgkmcnt(7)
	v_mfma_f32_16x16x32_bf16 v[126:129], v[138:141], v[154:157], v[126:129]
	v_mfma_f32_16x16x32_bf16 v[122:125], v[146:149], v[154:157], v[122:125]
	s_waitcnt lgkmcnt(5)
	v_mfma_f32_16x16x32_bf16 v[118:121], v[138:141], v[162:165], v[118:121]
	v_mfma_f32_16x16x32_bf16 v[114:117], v[146:149], v[162:165], v[114:117]
	s_waitcnt lgkmcnt(3)
	v_mfma_f32_16x16x32_bf16 v[110:113], v[138:141], v[170:173], v[110:113]
	s_waitcnt lgkmcnt(1)
	v_mfma_f32_16x16x32_bf16 v[102:105], v[138:141], v[178:181], v[102:105]
	v_mfma_f32_16x16x32_bf16 v[98:101], v[146:149], v[178:181], v[98:101]
	v_mfma_f32_16x16x32_bf16 v[126:129], v[142:145], v[158:161], v[126:129]
	v_mfma_f32_16x16x32_bf16 v[122:125], v[150:153], v[158:161], v[122:125]
	v_mfma_f32_16x16x32_bf16 v[118:121], v[142:145], v[166:169], v[118:121]
	v_mfma_f32_16x16x32_bf16 v[114:117], v[150:153], v[166:169], v[114:117]
	v_mfma_f32_16x16x32_bf16 v[110:113], v[142:145], v[174:177], v[110:113]
	v_mfma_f32_16x16x32_bf16 v[106:109], v[146:149], v[170:173], v[106:109]
	s_waitcnt lgkmcnt(0)
	v_mfma_f32_16x16x32_bf16 v[102:105], v[142:145], v[182:185], v[102:105]
	v_mfma_f32_16x16x32_bf16 v[98:101], v[150:153], v[182:185], v[98:101]
	v_mfma_f32_16x16x32_bf16 v[186:189], v[150:153], v[174:177], v[106:109]
	s_setprio 0
	s_barrier
	s_nop 1
	ds_read_b128 v[106:109], v137 offset:16384
	ds_read_b128 v[220:223], v137 offset:17408
	ds_read_b128 v[224:227], v137 offset:18432
	ds_read_b128 v[228:231], v137 offset:19456
	s_barrier
	s_waitcnt lgkmcnt(0)
	s_setprio 1
	s_waitcnt lgkmcnt(1)
	v_mfma_f32_16x16x32_bf16 v[90:93], v[224:227], v[154:157], v[90:93]
	v_mfma_f32_16x16x32_bf16 v[86:89], v[106:109], v[162:165], v[86:89]
	v_mfma_f32_16x16x32_bf16 v[82:85], v[224:227], v[162:165], v[82:85]
	v_mfma_f32_16x16x32_bf16 v[78:81], v[106:109], v[170:173], v[78:81]
	v_mfma_f32_16x16x32_bf16 v[74:77], v[224:227], v[170:173], v[74:77]
	v_mfma_f32_16x16x32_bf16 v[66:69], v[224:227], v[178:181], v[66:69]
	v_mfma_f32_16x16x32_bf16 v[94:97], v[106:109], v[154:157], v[94:97]
	s_waitcnt lgkmcnt(0)
	v_mfma_f32_16x16x32_bf16 v[90:93], v[228:231], v[158:161], v[90:93]
	v_mfma_f32_16x16x32_bf16 v[86:89], v[220:223], v[166:169], v[86:89]
	v_mfma_f32_16x16x32_bf16 v[82:85], v[228:231], v[166:169], v[82:85]
	v_mfma_f32_16x16x32_bf16 v[78:81], v[220:223], v[174:177], v[78:81]
	v_mfma_f32_16x16x32_bf16 v[74:77], v[228:231], v[174:177], v[74:77]
	v_mfma_f32_16x16x32_bf16 v[70:73], v[106:109], v[178:181], v[70:73]
	v_mfma_f32_16x16x32_bf16 v[66:69], v[228:231], v[182:185], v[66:69]
	v_mfma_f32_16x16x32_bf16 v[232:235], v[220:223], v[158:161], v[94:97]
	v_mfma_f32_16x16x32_bf16 v[154:157], v[220:223], v[182:185], v[70:73]
	s_setprio 0
	s_barrier
; #define WAIT_V(n) asm volatile("s_waitcnt vmcnt(" #n ")" ::: "memory")
; #define WAIT_L(n) asm volatile("s_waitcnt lgkmcnt(" #n ")" ::: "memory")
; #define BAR __builtin_amdgcn_s_barrier()
; #define LDA(dst, b, h)                                                                                   \
;   _Pragma("unroll") for (int m = 0; m < 4; ++m) _Pragma("unroll") for (int k = 0; k < 2; ++k) dst[m][k] = \
;       *reinterpret_cast<const bf16x8*>(aRd + ((b) * 2 + (h)) * 16384 + m * 2048 + k * 1024)
; #define LDB(dst, b, h)                                                                                   \
;   _Pragma("unroll") for (int n = 0; n < 2; ++n) _Pragma("unroll") for (int k = 0; k < 2; ++k) dst[n][k] = \
;       *reinterpret_cast<const bf16x8*>(bRd + ((b) * 2 + (h)) * 16384 + n * 2048 + k * 1024)
; template <int EPI> ...
;     ...
;     LDA(At, 0, 1);
;     WAIT_V(4);
;     BAR;
;     WAIT_L(0);
;     MMA(1, 0, At, B0);
;     MMA(1, 1, At, B1);
;     BAR;
;   }
;   {
;     LDB(B0, 1, 0);
;     LDA(At, 1, 0);
;     WAIT_V(2);
;     BAR;
;     WAIT_L(0);
;     MMA(0, 0, At, B0);
	s_nop 2
	ds_read_b128 v[70:73], v136 offset:16384
	ds_read_b128 v[94:97], v136 offset:17408
	ds_read_b128 v[158:161], v136 offset:18432
	ds_read_b128 v[162:165], v136 offset:19456
	ds_read_b128 v[166:169], v136 offset:20480
	ds_read_b128 v[170:173], v136 offset:21504
	ds_read_b128 v[174:177], v136 offset:22528
	ds_read_b128 v[178:181], v136 offset:23552
	s_waitcnt vmcnt(4)
	s_barrier
	s_waitcnt lgkmcnt(0)
	s_setprio 1
	s_waitcnt lgkmcnt(7)
	v_mfma_f32_16x16x32_bf16 v[62:65], v[138:141], v[70:73], v[62:65]
	s_waitcnt lgkmcnt(5)
	v_mfma_f32_16x16x32_bf16 v[54:57], v[138:141], v[158:161], v[54:57]
	v_mfma_f32_16x16x32_bf16 v[50:53], v[146:149], v[158:161], v[50:53]
	s_waitcnt lgkmcnt(1)
	v_mfma_f32_16x16x32_bf16 v[38:41], v[138:141], v[174:177], v[38:41]
	v_mfma_f32_16x16x32_bf16 v[62:65], v[142:145], v[94:97], v[62:65]
	v_mfma_f32_16x16x32_bf16 v[58:61], v[146:149], v[70:73], v[58:61]
	v_mfma_f32_16x16x32_bf16 v[54:57], v[142:145], v[162:165], v[54:57]
	v_mfma_f32_16x16x32_bf16 v[50:53], v[150:153], v[162:165], v[50:53]
	v_mfma_f32_16x16x32_bf16 v[46:49], v[138:141], v[166:169], v[46:49]
	v_mfma_f32_16x16x32_bf16 v[42:45], v[146:149], v[166:169], v[42:45]
	s_waitcnt lgkmcnt(0)
	v_mfma_f32_16x16x32_bf16 v[38:41], v[142:145], v[178:181], v[38:41]
	v_mfma_f32_16x16x32_bf16 v[34:37], v[146:149], v[174:177], v[34:37]
	v_mfma_f32_16x16x32_bf16 v[182:185], v[150:153], v[94:97], v[58:61]
	v_mfma_f32_16x16x32_bf16 v[236:239], v[142:145], v[170:173], v[46:49]
	v_mfma_f32_16x16x32_bf16 v[240:243], v[150:153], v[170:173], v[42:45]
	v_mfma_f32_16x16x32_bf16 v[138:141], v[150:153], v[178:181], v[34:37]
	s_setprio 0
	s_setprio 1
	v_mfma_f32_16x16x32_bf16 v[30:33], v[106:109], v[70:73], v[30:33]
	v_mfma_f32_16x16x32_bf16 v[26:29], v[224:227], v[70:73], v[26:29]
	v_mfma_f32_16x16x32_bf16 v[22:25], v[106:109], v[158:161], v[22:25]
	v_mfma_f32_16x16x32_bf16 v[18:21], v[224:227], v[158:161], v[18:21]
	v_mfma_f32_16x16x32_bf16 v[14:17], v[106:109], v[166:169], v[14:17]
	v_mfma_f32_16x16x32_bf16 v[10:13], v[224:227], v[166:169], v[10:13]
	v_mfma_f32_16x16x32_bf16 v[6:9], v[106:109], v[174:177], v[6:9]
	v_mfma_f32_16x16x32_bf16 v[2:5], v[224:227], v[174:177], v[2:5]
	v_mfma_f32_16x16x32_bf16 v[142:145], v[220:223], v[94:97], v[30:33]
	v_mfma_f32_16x16x32_bf16 v[146:149], v[228:231], v[94:97], v[26:29]
	v_mfma_f32_16x16x32_bf16 v[150:153], v[220:223], v[162:165], v[22:25]
	v_mfma_f32_16x16x32_bf16 v[158:161], v[228:231], v[162:165], v[18:21]
	v_mfma_f32_16x16x32_bf16 v[162:165], v[220:223], v[170:173], v[14:17]
	v_mfma_f32_16x16x32_bf16 v[166:169], v[228:231], v[170:173], v[10:13]
	v_mfma_f32_16x16x32_bf16 v[170:173], v[220:223], v[178:181], v[6:9]
	v_mfma_f32_16x16x32_bf16 v[174:177], v[228:231], v[178:181], v[2:5]
	s_setprio 0
	s_barrier
	ds_read_b128 v[18:21], v137 offset:32768
	ds_read_b128 v[22:25], v137 offset:33792
	ds_read_b128 v[26:29], v137 offset:34816
	ds_read_b128 v[178:181], v137 offset:35840
	ds_read_b128 v[46:49], v136 offset:32768
	ds_read_b128 v[58:61], v136 offset:33792
	ds_read_b128 v[70:73], v136 offset:34816
	ds_read_b128 v[220:223], v136 offset:35840
	ds_read_b128 v[224:227], v136 offset:36864
	ds_read_b128 v[228:231], v136 offset:37888
	ds_read_b128 v[244:247], v136 offset:38912
	ds_read_b128 v[248:251], v136 offset:39936
	s_waitcnt vmcnt(2)
	s_barrier
	s_waitcnt lgkmcnt(0)
	s_setprio 1
	s_waitcnt lgkmcnt(7)
	v_mfma_f32_16x16x32_bf16 v[2:5], v[18:21], v[46:49], v[126:129]
	s_waitcnt lgkmcnt(6)
	v_mfma_f32_16x16x32_bf16 v[94:97], v[22:25], v[58:61], v[2:5]
	v_mfma_f32_16x16x32_bf16 v[2:5], v[26:29], v[46:49], v[122:125]
	v_mfma_f32_16x16x32_bf16 v[106:109], v[178:181], v[58:61], v[2:5]
	s_waitcnt lgkmcnt(5)
	v_mfma_f32_16x16x32_bf16 v[2:5], v[18:21], v[70:73], v[118:121]
	s_waitcnt lgkmcnt(4)
	v_mfma_f32_16x16x32_bf16 v[30:33], v[22:25], v[220:223], v[2:5]
	v_mfma_f32_16x16x32_bf16 v[2:5], v[26:29], v[70:73], v[114:117]
	v_mfma_f32_16x16x32_bf16 v[42:45], v[178:181], v[220:223], v[2:5]
	s_waitcnt lgkmcnt(3)
	v_mfma_f32_16x16x32_bf16 v[2:5], v[18:21], v[224:227], v[110:113]
	s_waitcnt lgkmcnt(2)
	v_mfma_f32_16x16x32_bf16 v[10:13], v[22:25], v[228:231], v[2:5]
	v_mfma_f32_16x16x32_bf16 v[2:5], v[26:29], v[224:227], v[186:189]
	v_mfma_f32_16x16x32_bf16 v[14:17], v[178:181], v[228:231], v[2:5]
	s_waitcnt lgkmcnt(1)
	v_mfma_f32_16x16x32_bf16 v[2:5], v[18:21], v[244:247], v[102:105]
	v_mfma_f32_16x16x32_bf16 v[6:9], v[26:29], v[244:247], v[98:101]
	s_waitcnt lgkmcnt(0)
	v_mfma_f32_16x16x32_bf16 v[2:5], v[22:25], v[248:251], v[2:5]
	v_mfma_f32_16x16x32_bf16 v[6:9], v[178:181], v[248:251], v[6:9]
	s_setprio 0
	s_barrier
; #define WAIT_V(n) asm volatile("s_waitcnt vmcnt(" #n ")" ::: "memory")
; #define WAIT_L(n) asm volatile("s_waitcnt lgkmcnt(" #n ")" ::: "memory")
; #define BAR __builtin_amdgcn_s_barrier()
; #define LDA(dst, b, h)                                                                                   \
;   _Pragma("unroll") for (int m = 0; m < 4; ++m) _Pragma("unroll") for (int k = 0; k < 2; ++k) dst[m][k] = \
;       *reinterpret_cast<const bf16x8*>(aRd + ((b) * 2 + (h)) * 16384 + m * 2048 + k * 1024)
; #define LDB(dst, b, h)                                                                                   \
;   _Pragma("unroll") for (int n = 0; n < 2; ++n) _Pragma("unroll") for (int k = 0; k < 2; ++k) dst[n][k] = \
;       *reinterpret_cast<const bf16x8*>(bRd + ((b) * 2 + (h)) * 16384 + n * 2048 + k * 1024)
; template <int EPI> ...
;     ...
;     BAR;
;     LDB(B1, 1, 1);
;     WAIT_V(0);
;     BAR;
;     WAIT_L(0);
;     MMA(0, 1, At, B1);
;     BAR;
;     LDA(At, 1, 1);
;     BAR;
;     WAIT_L(0);
;     MMA(1, 0, At, B0);
;     MMA(1, 1, At, B1);
;     BAR;
;   }
;   if (wr == 0) BAR;
;   if (nAb) {
	ds_read_b128 v[102:105], v137 offset:49152
	ds_read_b128 v[186:189], v137 offset:50176
	ds_read_b128 v[196:199], v137 offset:51200
	ds_read_b128 v[212:215], v137 offset:52224
	s_waitcnt vmcnt(0)
	s_barrier
	s_waitcnt lgkmcnt(0)
	s_setprio 1
	s_waitcnt lgkmcnt(3)
	v_mfma_f32_16x16x32_bf16 v[34:37], v[102:105], v[46:49], v[232:235]
	s_waitcnt lgkmcnt(1)
	v_mfma_f32_16x16x32_bf16 v[46:49], v[196:199], v[46:49], v[90:93]
	v_mfma_f32_16x16x32_bf16 v[74:77], v[196:199], v[224:227], v[74:77]
	v_mfma_f32_16x16x32_bf16 v[34:37], v[186:189], v[58:61], v[34:37]
	s_waitcnt lgkmcnt(0)
	v_mfma_f32_16x16x32_bf16 v[46:49], v[212:215], v[58:61], v[46:49]
	v_mfma_f32_16x16x32_bf16 v[58:61], v[102:105], v[70:73], v[86:89]
	v_mfma_f32_16x16x32_bf16 v[70:73], v[196:199], v[70:73], v[82:85]
	v_mfma_f32_16x16x32_bf16 v[78:81], v[102:105], v[224:227], v[78:81]
	v_mfma_f32_16x16x32_bf16 v[86:89], v[212:215], v[228:231], v[74:77]
	v_mfma_f32_16x16x32_bf16 v[74:77], v[102:105], v[244:247], v[154:157]
	v_mfma_f32_16x16x32_bf16 v[66:69], v[196:199], v[244:247], v[66:69]
	v_mfma_f32_16x16x32_bf16 v[58:61], v[186:189], v[220:223], v[58:61]
	v_mfma_f32_16x16x32_bf16 v[70:73], v[212:215], v[220:223], v[70:73]
	v_mfma_f32_16x16x32_bf16 v[78:81], v[186:189], v[228:231], v[78:81]
	v_mfma_f32_16x16x32_bf16 v[98:101], v[186:189], v[248:251], v[74:77]
	v_mfma_f32_16x16x32_bf16 v[110:113], v[212:215], v[248:251], v[66:69]
	s_setprio 0
	s_barrier
	s_nop 0
	ds_read_b128 v[66:69], v136 offset:49152
	ds_read_b128 v[74:77], v136 offset:50176
	ds_read_b128 v[82:85], v136 offset:51200
	ds_read_b128 v[90:93], v136 offset:52224
	ds_read_b128 v[154:157], v136 offset:53248
	ds_read_b128 v[220:223], v136 offset:54272
	ds_read_b128 v[224:227], v136 offset:55296
	ds_read_b128 v[228:231], v136 offset:56320
	s_barrier
	s_waitcnt lgkmcnt(0)
	s_setprio 1
	s_waitcnt lgkmcnt(5)
	v_mfma_f32_16x16x32_bf16 v[50:53], v[26:29], v[82:85], v[50:53]
	v_mfma_f32_16x16x32_bf16 v[62:65], v[18:21], v[66:69], v[62:65]
	v_mfma_f32_16x16x32_bf16 v[54:57], v[18:21], v[82:85], v[54:57]
	s_waitcnt lgkmcnt(4)
	v_mfma_f32_16x16x32_bf16 v[118:121], v[178:181], v[90:93], v[50:53]
	s_waitcnt lgkmcnt(3)
	v_mfma_f32_16x16x32_bf16 v[50:53], v[18:21], v[154:157], v[236:239]
	s_waitcnt lgkmcnt(1)
	v_mfma_f32_16x16x32_bf16 v[18:21], v[18:21], v[224:227], v[38:41]
	v_mfma_f32_16x16x32_bf16 v[122:125], v[22:25], v[74:77], v[62:65]
	v_mfma_f32_16x16x32_bf16 v[62:65], v[26:29], v[66:69], v[182:185]
	v_mfma_f32_16x16x32_bf16 v[114:117], v[22:25], v[90:93], v[54:57]
	v_mfma_f32_16x16x32_bf16 v[50:53], v[22:25], v[220:223], v[50:53]
	v_mfma_f32_16x16x32_bf16 v[54:57], v[26:29], v[154:157], v[240:243]
	s_waitcnt lgkmcnt(0)
	v_mfma_f32_16x16x32_bf16 v[18:21], v[22:25], v[228:231], v[18:21]
	v_mfma_f32_16x16x32_bf16 v[22:25], v[26:29], v[224:227], v[138:141]
	v_mfma_f32_16x16x32_bf16 v[126:129], v[178:181], v[74:77], v[62:65]
	v_mfma_f32_16x16x32_bf16 v[62:65], v[178:181], v[220:223], v[54:57]
	v_mfma_f32_16x16x32_bf16 v[22:25], v[178:181], v[228:231], v[22:25]
	s_setprio 0
	s_setprio 1
	v_mfma_f32_16x16x32_bf16 v[26:29], v[102:105], v[66:69], v[142:145]
	v_mfma_f32_16x16x32_bf16 v[38:41], v[196:199], v[66:69], v[146:149]
	v_mfma_f32_16x16x32_bf16 v[54:57], v[102:105], v[82:85], v[150:153]
	v_mfma_f32_16x16x32_bf16 v[66:69], v[196:199], v[82:85], v[158:161]
	v_mfma_f32_16x16x32_bf16 v[26:29], v[186:189], v[74:77], v[26:29]
	v_mfma_f32_16x16x32_bf16 v[38:41], v[212:215], v[74:77], v[38:41]
	v_mfma_f32_16x16x32_bf16 v[54:57], v[186:189], v[90:93], v[54:57]
	v_mfma_f32_16x16x32_bf16 v[66:69], v[212:215], v[90:93], v[66:69]
	v_mfma_f32_16x16x32_bf16 v[74:77], v[102:105], v[154:157], v[162:165]
	v_mfma_f32_16x16x32_bf16 v[82:85], v[196:199], v[154:157], v[166:169]
	v_mfma_f32_16x16x32_bf16 v[90:93], v[102:105], v[224:227], v[170:173]
	v_mfma_f32_16x16x32_bf16 v[102:105], v[196:199], v[224:227], v[174:177]
	v_mfma_f32_16x16x32_bf16 v[74:77], v[186:189], v[220:223], v[74:77]
	v_mfma_f32_16x16x32_bf16 v[82:85], v[212:215], v[220:223], v[82:85]
	v_mfma_f32_16x16x32_bf16 v[90:93], v[186:189], v[228:231], v[90:93]
	v_mfma_f32_16x16x32_bf16 v[102:105], v[212:215], v[228:231], v[102:105]
	s_setprio 0
	s_movk_i32 s6, 0x100
	v_cmp_gt_u32_e32 vcc, s6, v133
	s_barrier
	s_and_saveexec_b64 s[12:13], vcc
	s_cbranch_execz .LBB0_206
	s_barrier

; #define WAIT_V(n) asm volatile("s_waitcnt vmcnt(" #n ")" ::: "memory")
; #define WAIT_L(n) asm volatile("s_waitcnt lgkmcnt(" #n ")" ::: "memory")
; #define BAR __builtin_amdgcn_s_barrier()
; #define SCHED __builtin_amdgcn_sched_barrier(0)
; #define STAGE_A(b, h, kt)                                        \
;   do {                                                           \
;     const char* _g = Ab + (h) * halfK + (long)(kt) * 128;        \
;     GLDS2(_g, (unsigned)(((b) * 2 + (h)) * 16384));              \
;   } while (0)
; #define STAGE_B(b, h, kt)                                        \
;   do {                                                           \
;     const char* _g = Bb + (h) * halfK + (long)(kt) * 128;        \
;     GLDS2(_g, (unsigned)(65536 + ((b) * 2 + (h)) * 16384));      \
;   } while (0)
; #define LDA(dst, b, h)                                                                                   \
;   _Pragma("unroll") for (int m = 0; m < 4; ++m) _Pragma("unroll") for (int k = 0; k < 2; ++k) dst[m][k] = \
;       *reinterpret_cast<const bf16x8*>(aRd + ((b) * 2 + (h)) * 16384 + m * 2048 + k * 1024)
; #define LDB(dst, b, h)                                                                                   \
;   _Pragma("unroll") for (int n = 0; n < 2; ++n) _Pragma("unroll") for (int k = 0; k < 2; ++k) dst[n][k] = \
;       *reinterpret_cast<const bf16x8*>(bRd + ((b) * 2 + (h)) * 16384 + n * 2048 + k * 1024)
; template <int EPI> ...
;     ...
;     LDB(B0, 0, 0);
;     SCHED;
;     LDA(At, 0, 0);
;     STAGE_A(1, 1, t + 1);
;     WAIT_L(8);
;     BAR;
;     WAIT_L(0);
;     MMA(0, 0, At, B0);
;     BAR;
;     SCHED;
;     LDB(B1, 0, 1);
;     STAGE_B(0, 0, t + 2);
;     BAR;
;     WAIT_L(0);
;     MMA(0, 1, At, B1);
;     BAR;
;     LDA(At, 0, 1);
;     STAGE_A(0, 0, t + 2);
;     BAR;
;     WAIT_L(0);
;     MMA(1, 0, At, B0);
;     BAR;
;     SCHED;
;     STAGE_B(0, 1, t + 2);
;     WAIT_V(6);
;     BAR;
.LBB0_415:
	ds_read_b128 v[138:141], v136
	ds_read_b128 v[142:145], v136 offset:1024
	ds_read_b128 v[146:149], v136 offset:2048
	ds_read_b128 v[150:153], v136 offset:3072
	ds_read_b128 v[154:157], v135
	ds_read_b128 v[158:161], v135 offset:1024
	ds_read_b128 v[162:165], v135 offset:2048
	ds_read_b128 v[170:173], v135 offset:3072
	ds_read_b128 v[174:177], v135 offset:4096
	ds_read_b128 v[178:181], v135 offset:5120
	ds_read_b128 v[182:185], v135 offset:6144
	ds_read_b128 v[186:189], v135 offset:7168
	s_add_u32 s64, s10, s12
	s_addc_u32 s78, s11, s13
	s_add_u32 s74, s64, 0x80
	s_addc_u32 s75, s78, 0
	s_mov_b32 m0, s62
	s_nop 0
	global_load_lds_dwordx4 v132, s[74:75]
	s_nop 0
	s_mov_b32 m0, s59
	s_nop 0
	global_load_lds_dwordx4 v131, s[74:75]
	s_waitcnt lgkmcnt(8)
	s_barrier
	s_waitcnt lgkmcnt(0)
	s_setprio 1
	v_mfma_f32_16x16x32_bf16 v[126:129], v[138:141], v[154:157], v[126:129]
	v_mfma_f32_16x16x32_bf16 v[126:129], v[142:145], v[158:161], v[126:129]
	v_mfma_f32_16x16x32_bf16 v[122:125], v[146:149], v[154:157], v[122:125]
	v_mfma_f32_16x16x32_bf16 v[122:125], v[150:153], v[158:161], v[122:125]
	v_mfma_f32_16x16x32_bf16 v[118:121], v[138:141], v[162:165], v[118:121]
	v_mfma_f32_16x16x32_bf16 v[118:121], v[142:145], v[170:173], v[118:121]
	v_mfma_f32_16x16x32_bf16 v[114:117], v[146:149], v[162:165], v[114:117]
	v_mfma_f32_16x16x32_bf16 v[114:117], v[150:153], v[170:173], v[114:117]
	v_mfma_f32_16x16x32_bf16 v[110:113], v[138:141], v[174:177], v[110:113]
	v_mfma_f32_16x16x32_bf16 v[110:113], v[142:145], v[178:181], v[110:113]
	v_mfma_f32_16x16x32_bf16 v[106:109], v[146:149], v[174:177], v[106:109]
	v_mfma_f32_16x16x32_bf16 v[106:109], v[150:153], v[178:181], v[106:109]
	v_mfma_f32_16x16x32_bf16 v[102:105], v[138:141], v[182:185], v[102:105]
	v_mfma_f32_16x16x32_bf16 v[102:105], v[142:145], v[186:189], v[102:105]
	v_mfma_f32_16x16x32_bf16 v[98:101], v[146:149], v[182:185], v[98:101]
	v_mfma_f32_16x16x32_bf16 v[98:101], v[150:153], v[186:189], v[98:101]
	s_setprio 0
	s_barrier
	ds_read_b128 v[220:223], v136 offset:16384
	ds_read_b128 v[224:227], v136 offset:17408
	ds_read_b128 v[228:231], v136 offset:18432
	ds_read_b128 v[232:235], v136 offset:19456
	s_add_u32 s79, s72, s12
	s_addc_u32 s80, s73, s13
	s_add_u32 s74, s79, 0x100
	s_addc_u32 s75, s80, 0
	s_mov_b32 m0, s15
	s_nop 0
	global_load_lds_dwordx4 v132, s[74:75]
	s_nop 0
	s_mov_b32 m0, s33
	s_nop 0
	global_load_lds_dwordx4 v131, s[74:75]
	s_barrier
	s_waitcnt lgkmcnt(0)
	s_setprio 1
	v_mfma_f32_16x16x32_bf16 v[94:97], v[220:223], v[154:157], v[94:97]
	v_mfma_f32_16x16x32_bf16 v[94:97], v[224:227], v[158:161], v[94:97]
	v_mfma_f32_16x16x32_bf16 v[90:93], v[228:231], v[154:157], v[90:93]
	v_mfma_f32_16x16x32_bf16 v[90:93], v[232:235], v[158:161], v[90:93]
	v_mfma_f32_16x16x32_bf16 v[86:89], v[220:223], v[162:165], v[86:89]
	v_mfma_f32_16x16x32_bf16 v[86:89], v[224:227], v[170:173], v[86:89]
	v_mfma_f32_16x16x32_bf16 v[82:85], v[228:231], v[162:165], v[82:85]
	v_mfma_f32_16x16x32_bf16 v[82:85], v[232:235], v[170:173], v[82:85]
	v_mfma_f32_16x16x32_bf16 v[78:81], v[220:223], v[174:177], v[78:81]
	v_mfma_f32_16x16x32_bf16 v[78:81], v[224:227], v[178:181], v[78:81]
	v_mfma_f32_16x16x32_bf16 v[74:77], v[228:231], v[174:177], v[74:77]
	v_mfma_f32_16x16x32_bf16 v[74:77], v[232:235], v[178:181], v[74:77]
	v_mfma_f32_16x16x32_bf16 v[70:73], v[220:223], v[182:185], v[70:73]
	v_mfma_f32_16x16x32_bf16 v[70:73], v[224:227], v[186:189], v[70:73]
	v_mfma_f32_16x16x32_bf16 v[66:69], v[228:231], v[182:185], v[66:69]
	v_mfma_f32_16x16x32_bf16 v[66:69], v[232:235], v[186:189], v[66:69]
	s_setprio 0
	s_barrier
	ds_read_b128 v[154:157], v135 offset:16384
	ds_read_b128 v[158:161], v135 offset:17408
	ds_read_b128 v[162:165], v135 offset:18432
	ds_read_b128 v[170:173], v135 offset:19456
	ds_read_b128 v[174:177], v135 offset:20480
	ds_read_b128 v[178:181], v135 offset:21504
	ds_read_b128 v[182:185], v135 offset:22528
	ds_read_b128 v[186:189], v135 offset:23552
	s_add_u32 s81, s18, s12
	s_addc_u32 s82, s19, s13
	s_add_u32 s74, s81, 0x100
	s_addc_u32 s75, s82, 0
	s_mov_b32 m0, s2
	s_nop 0
	global_load_lds_dwordx4 v132, s[74:75]
	s_nop 0
	s_mov_b32 m0, s41
	s_nop 0
	global_load_lds_dwordx4 v131, s[74:75]
	s_barrier
	s_waitcnt lgkmcnt(0)
	s_setprio 1
	v_mfma_f32_16x16x32_bf16 v[62:65], v[138:141], v[154:157], v[62:65]
	v_mfma_f32_16x16x32_bf16 v[62:65], v[142:145], v[158:161], v[62:65]
	v_mfma_f32_16x16x32_bf16 v[58:61], v[146:149], v[154:157], v[58:61]
	v_mfma_f32_16x16x32_bf16 v[58:61], v[150:153], v[158:161], v[58:61]
	v_mfma_f32_16x16x32_bf16 v[54:57], v[138:141], v[162:165], v[54:57]
	v_mfma_f32_16x16x32_bf16 v[54:57], v[142:145], v[170:173], v[54:57]
	v_mfma_f32_16x16x32_bf16 v[50:53], v[146:149], v[162:165], v[50:53]
	v_mfma_f32_16x16x32_bf16 v[50:53], v[150:153], v[170:173], v[50:53]
	v_mfma_f32_16x16x32_bf16 v[46:49], v[138:141], v[174:177], v[46:49]
	v_mfma_f32_16x16x32_bf16 v[46:49], v[142:145], v[178:181], v[46:49]
	v_mfma_f32_16x16x32_bf16 v[42:45], v[146:149], v[174:177], v[42:45]
	v_mfma_f32_16x16x32_bf16 v[42:45], v[150:153], v[178:181], v[42:45]
	v_mfma_f32_16x16x32_bf16 v[38:41], v[138:141], v[182:185], v[38:41]
	v_mfma_f32_16x16x32_bf16 v[38:41], v[142:145], v[186:189], v[38:41]
	v_mfma_f32_16x16x32_bf16 v[34:37], v[146:149], v[182:185], v[34:37]
	v_mfma_f32_16x16x32_bf16 v[34:37], v[150:153], v[186:189], v[34:37]
	s_setprio 0
	s_barrier
	s_add_u32 s83, s6, s12
	s_addc_u32 s84, s7, s13
	s_add_u32 s74, s83, 0x100
	s_addc_u32 s75, s84, 0
	s_mov_b32 m0, s38
	s_nop 0
	global_load_lds_dwordx4 v132, s[74:75]
	s_nop 0
	s_mov_b32 m0, s39
	s_nop 0
	global_load_lds_dwordx4 v131, s[74:75]
	s_waitcnt vmcnt(6)
	s_barrier
; #define WAIT_L(n) asm volatile("s_waitcnt lgkmcnt(" #n ")" ::: "memory")
; #define BAR __builtin_amdgcn_s_barrier()
; #define SCHED __builtin_amdgcn_sched_barrier(0)
; #define STAGE_A(b, h, kt)                                        \
;   do {                                                           \
;     const char* _g = Ab + (h) * halfK + (long)(kt) * 128;        \
;     GLDS2(_g, (unsigned)(((b) * 2 + (h)) * 16384));              \
;   } while (0)
; #define STAGE_B(b, h, kt)                                        \
;   do {                                                           \
;     const char* _g = Bb + (h) * halfK + (long)(kt) * 128;        \
;     GLDS2(_g, (unsigned)(65536 + ((b) * 2 + (h)) * 16384));      \
;   } while (0)
; #define LDA(dst, b, h)                                                                                   \
;   _Pragma("unroll") for (int m = 0; m < 4; ++m) _Pragma("unroll") for (int k = 0; k < 2; ++k) dst[m][k] = \
;       *reinterpret_cast<const bf16x8*>(aRd + ((b) * 2 + (h)) * 16384 + m * 2048 + k * 1024)
; #define LDB(dst, b, h)                                                                                   \
;   _Pragma("unroll") for (int n = 0; n < 2; ++n) _Pragma("unroll") for (int k = 0; k < 2; ++k) dst[n][k] = \
;       *reinterpret_cast<const bf16x8*>(bRd + ((b) * 2 + (h)) * 16384 + n * 2048 + k * 1024)
; template <int EPI> ...
;     ...
;     MMA(1, 1, At, B1);
;     BAR;
;     LDB(B0, 1, 0);
;     SCHED;
;     LDA(At, 1, 0);
;     STAGE_A(0, 1, t + 2);
;     WAIT_L(8);
;     BAR;
;     WAIT_L(0);
;     MMA(0, 0, At, B0);
;     BAR;
;     SCHED;
;     LDB(B1, 1, 1);
;     STAGE_B(1, 0, t + 3);
;     BAR;
;     WAIT_L(0);
;     MMA(0, 1, At, B1);
;     BAR;
;     LDA(At, 1, 1);
;     STAGE_A(1, 0, t + 3);
;     BAR;
;     WAIT_L(0);
;     MMA(1, 0, At, B0);
;     BAR;
;     SCHED;
;     STAGE_B(1, 1, t + 3);
	s_setprio 1
	v_mfma_f32_16x16x32_bf16 v[30:33], v[220:223], v[154:157], v[30:33]
	v_mfma_f32_16x16x32_bf16 v[30:33], v[224:227], v[158:161], v[30:33]
	v_mfma_f32_16x16x32_bf16 v[26:29], v[228:231], v[154:157], v[26:29]
	v_mfma_f32_16x16x32_bf16 v[26:29], v[232:235], v[158:161], v[26:29]
	v_mfma_f32_16x16x32_bf16 v[22:25], v[220:223], v[162:165], v[22:25]
	v_mfma_f32_16x16x32_bf16 v[22:25], v[224:227], v[170:173], v[22:25]
	v_mfma_f32_16x16x32_bf16 v[18:21], v[228:231], v[162:165], v[18:21]
	v_mfma_f32_16x16x32_bf16 v[18:21], v[232:235], v[170:173], v[18:21]
	v_mfma_f32_16x16x32_bf16 v[14:17], v[220:223], v[174:177], v[14:17]
	v_mfma_f32_16x16x32_bf16 v[14:17], v[224:227], v[178:181], v[14:17]
	v_mfma_f32_16x16x32_bf16 v[10:13], v[228:231], v[174:177], v[10:13]
	v_mfma_f32_16x16x32_bf16 v[10:13], v[232:235], v[178:181], v[10:13]
	v_mfma_f32_16x16x32_bf16 v[6:9], v[220:223], v[182:185], v[6:9]
	v_mfma_f32_16x16x32_bf16 v[6:9], v[224:227], v[186:189], v[6:9]
	v_mfma_f32_16x16x32_bf16 v[2:5], v[228:231], v[182:185], v[2:5]
	v_mfma_f32_16x16x32_bf16 v[2:5], v[232:235], v[186:189], v[2:5]
	s_setprio 0
	s_barrier
	ds_read_b128 v[138:141], v136 offset:32768
	ds_read_b128 v[142:145], v136 offset:33792
	ds_read_b128 v[146:149], v136 offset:34816
	ds_read_b128 v[150:153], v136 offset:35840
	ds_read_b128 v[154:157], v135 offset:32768
	ds_read_b128 v[158:161], v135 offset:33792
	ds_read_b128 v[162:165], v135 offset:34816
	ds_read_b128 v[170:173], v135 offset:35840
	ds_read_b128 v[174:177], v135 offset:36864
	ds_read_b128 v[178:181], v135 offset:37888
	ds_read_b128 v[182:185], v135 offset:38912
	ds_read_b128 v[186:189], v135 offset:39936
	s_add_u32 s74, s64, 0x100
	s_addc_u32 s75, s78, 0
	s_mov_b32 m0, s47
	s_nop 0
	global_load_lds_dwordx4 v132, s[74:75]
	s_nop 0
	s_mov_b32 m0, s48
	s_nop 0
	global_load_lds_dwordx4 v131, s[74:75]
	s_waitcnt lgkmcnt(8)
	s_barrier
	s_waitcnt lgkmcnt(0)
	s_setprio 1
	v_mfma_f32_16x16x32_bf16 v[126:129], v[138:141], v[154:157], v[126:129]
	v_mfma_f32_16x16x32_bf16 v[126:129], v[142:145], v[158:161], v[126:129]
	v_mfma_f32_16x16x32_bf16 v[122:125], v[146:149], v[154:157], v[122:125]
	v_mfma_f32_16x16x32_bf16 v[122:125], v[150:153], v[158:161], v[122:125]
	v_mfma_f32_16x16x32_bf16 v[118:121], v[138:141], v[162:165], v[118:121]
	v_mfma_f32_16x16x32_bf16 v[118:121], v[142:145], v[170:173], v[118:121]
	v_mfma_f32_16x16x32_bf16 v[114:117], v[146:149], v[162:165], v[114:117]
	v_mfma_f32_16x16x32_bf16 v[114:117], v[150:153], v[170:173], v[114:117]
	v_mfma_f32_16x16x32_bf16 v[110:113], v[138:141], v[174:177], v[110:113]
	v_mfma_f32_16x16x32_bf16 v[110:113], v[142:145], v[178:181], v[110:113]
	v_mfma_f32_16x16x32_bf16 v[106:109], v[146:149], v[174:177], v[106:109]
	v_mfma_f32_16x16x32_bf16 v[106:109], v[150:153], v[178:181], v[106:109]
	v_mfma_f32_16x16x32_bf16 v[102:105], v[138:141], v[182:185], v[102:105]
	v_mfma_f32_16x16x32_bf16 v[102:105], v[142:145], v[186:189], v[102:105]
	v_mfma_f32_16x16x32_bf16 v[98:101], v[146:149], v[182:185], v[98:101]
	v_mfma_f32_16x16x32_bf16 v[98:101], v[150:153], v[186:189], v[98:101]
	s_setprio 0
	s_barrier
	ds_read_b128 v[220:223], v136 offset:49152
	ds_read_b128 v[224:227], v136 offset:50176
	ds_read_b128 v[228:231], v136 offset:51200
	ds_read_b128 v[232:235], v136 offset:52224
	s_add_u32 s74, s79, 0x180
	s_addc_u32 s75, s80, 0
	s_mov_b32 m0, s50
	s_nop 0
	global_load_lds_dwordx4 v132, s[74:75]
	s_nop 0
	s_mov_b32 m0, s51
	s_nop 0
	global_load_lds_dwordx4 v131, s[74:75]
	s_barrier
	s_waitcnt lgkmcnt(0)
	s_setprio 1
	v_mfma_f32_16x16x32_bf16 v[94:97], v[220:223], v[154:157], v[94:97]
	v_mfma_f32_16x16x32_bf16 v[94:97], v[224:227], v[158:161], v[94:97]
	v_mfma_f32_16x16x32_bf16 v[90:93], v[228:231], v[154:157], v[90:93]
	v_mfma_f32_16x16x32_bf16 v[90:93], v[232:235], v[158:161], v[90:93]
	v_mfma_f32_16x16x32_bf16 v[86:89], v[220:223], v[162:165], v[86:89]
	v_mfma_f32_16x16x32_bf16 v[86:89], v[224:227], v[170:173], v[86:89]
	v_mfma_f32_16x16x32_bf16 v[82:85], v[228:231], v[162:165], v[82:85]
	v_mfma_f32_16x16x32_bf16 v[82:85], v[232:235], v[170:173], v[82:85]
	v_mfma_f32_16x16x32_bf16 v[78:81], v[220:223], v[174:177], v[78:81]
	v_mfma_f32_16x16x32_bf16 v[78:81], v[224:227], v[178:181], v[78:81]
	v_mfma_f32_16x16x32_bf16 v[74:77], v[228:231], v[174:177], v[74:77]
	v_mfma_f32_16x16x32_bf16 v[74:77], v[232:235], v[178:181], v[74:77]
	v_mfma_f32_16x16x32_bf16 v[70:73], v[220:223], v[182:185], v[70:73]
	v_mfma_f32_16x16x32_bf16 v[70:73], v[224:227], v[186:189], v[70:73]
	v_mfma_f32_16x16x32_bf16 v[66:69], v[228:231], v[182:185], v[66:69]
	v_mfma_f32_16x16x32_bf16 v[66:69], v[232:235], v[186:189], v[66:69]
	s_setprio 0
	s_barrier
	ds_read_b128 v[154:157], v135 offset:49152
	ds_read_b128 v[158:161], v135 offset:50176
	ds_read_b128 v[162:165], v135 offset:51200
	ds_read_b128 v[170:173], v135 offset:52224
	ds_read_b128 v[174:177], v135 offset:53248
	ds_read_b128 v[178:181], v135 offset:54272
	ds_read_b128 v[182:185], v135 offset:55296
	ds_read_b128 v[186:189], v135 offset:56320
	s_add_u32 s74, s81, 0x180
	s_addc_u32 s75, s82, 0
	s_mov_b32 m0, s58
	s_nop 0
	global_load_lds_dwordx4 v132, s[74:75]
	s_nop 0
	s_mov_b32 m0, s63
	s_nop 0
	global_load_lds_dwordx4 v131, s[74:75]
	s_barrier
; #define WAIT_V(n) asm volatile("s_waitcnt vmcnt(" #n ")" ::: "memory")
; #define WAIT_L(n) asm volatile("s_waitcnt lgkmcnt(" #n ")" ::: "memory")
; #define BAR __builtin_amdgcn_s_barrier()
; #define SCHED __builtin_amdgcn_sched_barrier(0)
; #define STAGE_A(b, h, kt)                                        \
;   do {                                                           \
;     const char* _g = Ab + (h) * halfK + (long)(kt) * 128;        \
;     GLDS2(_g, (unsigned)(((b) * 2 + (h)) * 16384));              \
;   } while (0)
; #define STAGE_B(b, h, kt)                                        \
;   do {                                                           \
;     const char* _g = Bb + (h) * halfK + (long)(kt) * 128;        \
;     GLDS2(_g, (unsigned)(65536 + ((b) * 2 + (h)) * 16384));      \
;   } while (0)
; #define LDA(dst, b, h)                                                                                   \
;   _Pragma("unroll") for (int m = 0; m < 4; ++m) _Pragma("unroll") for (int k = 0; k < 2; ++k) dst[m][k] = \
;       *reinterpret_cast<const bf16x8*>(aRd + ((b) * 2 + (h)) * 16384 + m * 2048 + k * 1024)
; #define LDB(dst, b, h)                                                                                   \
;   _Pragma("unroll") for (int n = 0; n < 2; ++n) _Pragma("unroll") for (int k = 0; k < 2; ++k) dst[n][k] = \
;       *reinterpret_cast<const bf16x8*>(bRd + ((b) * 2 + (h)) * 16384 + n * 2048 + k * 1024)
; template <int EPI> ...
;     ...
;     MMA(1, 0, At, B0);
;     BAR;
;     SCHED;
;     STAGE_B(1, 1, t + 3);
;     WAIT_V(6);
;     BAR;
;     MMA(1, 1, At, B1);
;     BAR;
;   }
;   {
;     LDB(B0, 0, 0);
;     LDA(At, 0, 0);
;     STAGE_A(1, 1, nt - 1);
;     BAR;
;     WAIT_L(0);
;     MMA(0, 0, At, B0);
;     BAR;
;     LDB(B1, 0, 1);
;     BAR;
;     WAIT_L(0);
;     MMA(0, 1, At, B1);
;     BAR;
	s_waitcnt lgkmcnt(0)
	s_setprio 1
	v_mfma_f32_16x16x32_bf16 v[62:65], v[138:141], v[154:157], v[62:65]
	v_mfma_f32_16x16x32_bf16 v[62:65], v[142:145], v[158:161], v[62:65]
	v_mfma_f32_16x16x32_bf16 v[58:61], v[146:149], v[154:157], v[58:61]
	v_mfma_f32_16x16x32_bf16 v[58:61], v[150:153], v[158:161], v[58:61]
	v_mfma_f32_16x16x32_bf16 v[54:57], v[138:141], v[162:165], v[54:57]
	v_mfma_f32_16x16x32_bf16 v[54:57], v[142:145], v[170:173], v[54:57]
	v_mfma_f32_16x16x32_bf16 v[50:53], v[146:149], v[162:165], v[50:53]
	v_mfma_f32_16x16x32_bf16 v[50:53], v[150:153], v[170:173], v[50:53]
	v_mfma_f32_16x16x32_bf16 v[46:49], v[138:141], v[174:177], v[46:49]
	v_mfma_f32_16x16x32_bf16 v[46:49], v[142:145], v[178:181], v[46:49]
	v_mfma_f32_16x16x32_bf16 v[42:45], v[146:149], v[174:177], v[42:45]
	v_mfma_f32_16x16x32_bf16 v[42:45], v[150:153], v[178:181], v[42:45]
	v_mfma_f32_16x16x32_bf16 v[38:41], v[138:141], v[182:185], v[38:41]
	v_mfma_f32_16x16x32_bf16 v[38:41], v[142:145], v[186:189], v[38:41]
	v_mfma_f32_16x16x32_bf16 v[34:37], v[146:149], v[182:185], v[34:37]
	v_mfma_f32_16x16x32_bf16 v[34:37], v[150:153], v[186:189], v[34:37]
	s_setprio 0
	s_barrier
	s_add_u32 s74, s83, 0x180
	s_addc_u32 s75, s84, 0
	s_mov_b32 m0, s8
	s_nop 0
	global_load_lds_dwordx4 v132, s[74:75]
	s_nop 0
	s_mov_b32 m0, s9
	s_nop 0
	global_load_lds_dwordx4 v131, s[74:75]
	s_waitcnt vmcnt(6)
	s_barrier
	s_setprio 1
	v_mfma_f32_16x16x32_bf16 v[30:33], v[220:223], v[154:157], v[30:33]
	v_mfma_f32_16x16x32_bf16 v[30:33], v[224:227], v[158:161], v[30:33]
	v_mfma_f32_16x16x32_bf16 v[26:29], v[228:231], v[154:157], v[26:29]
	v_mfma_f32_16x16x32_bf16 v[26:29], v[232:235], v[158:161], v[26:29]
	v_mfma_f32_16x16x32_bf16 v[22:25], v[220:223], v[162:165], v[22:25]
	v_mfma_f32_16x16x32_bf16 v[22:25], v[224:227], v[170:173], v[22:25]
	v_mfma_f32_16x16x32_bf16 v[18:21], v[228:231], v[162:165], v[18:21]
	v_mfma_f32_16x16x32_bf16 v[18:21], v[232:235], v[170:173], v[18:21]
	v_mfma_f32_16x16x32_bf16 v[14:17], v[220:223], v[174:177], v[14:17]
	v_mfma_f32_16x16x32_bf16 v[14:17], v[224:227], v[178:181], v[14:17]
	v_mfma_f32_16x16x32_bf16 v[10:13], v[228:231], v[174:177], v[10:13]
	v_mfma_f32_16x16x32_bf16 v[10:13], v[232:235], v[178:181], v[10:13]
	v_mfma_f32_16x16x32_bf16 v[6:9], v[220:223], v[182:185], v[6:9]
	v_mfma_f32_16x16x32_bf16 v[6:9], v[224:227], v[186:189], v[6:9]
	v_mfma_f32_16x16x32_bf16 v[2:5], v[228:231], v[182:185], v[2:5]
	v_mfma_f32_16x16x32_bf16 v[2:5], v[232:235], v[186:189], v[2:5]
	s_setprio 0
	s_add_i32 s37, s37, 2
	s_add_u32 s12, s12, 0x100
	s_addc_u32 s13, s13, 0
	s_cmp_lt_u32 s37, 28
	s_barrier
	s_cbranch_scc1 .LBB0_415
	ds_read_b128 v[138:141], v136
	ds_read_b128 v[142:145], v136 offset:1024
	ds_read_b128 v[146:149], v136 offset:2048
	ds_read_b128 v[150:153], v136 offset:3072
	ds_read_b128 v[154:157], v135
	ds_read_b128 v[158:161], v135 offset:1024
	ds_read_b128 v[162:165], v135 offset:2048
	ds_read_b128 v[170:173], v135 offset:3072
	ds_read_b128 v[174:177], v135 offset:4096
	ds_read_b128 v[178:181], v135 offset:5120
	ds_read_b128 v[182:185], v135 offset:6144
	ds_read_b128 v[186:189], v135 offset:7168
	s_add_u32 s6, s18, 0x80f80
	s_addc_u32 s7, s19, 0
	s_mov_b32 m0, s62
	s_nop 0
	global_load_lds_dwordx4 v132, s[6:7]
	s_nop 0
	s_mov_b32 m0, s59
	s_nop 0
	global_load_lds_dwordx4 v131, s[6:7]
	s_barrier
	s_waitcnt lgkmcnt(0)
	s_setprio 1
	v_mfma_f32_16x16x32_bf16 v[126:129], v[138:141], v[154:157], v[126:129]
	v_mfma_f32_16x16x32_bf16 v[126:129], v[142:145], v[158:161], v[126:129]
	v_mfma_f32_16x16x32_bf16 v[122:125], v[146:149], v[154:157], v[122:125]
	v_mfma_f32_16x16x32_bf16 v[122:125], v[150:153], v[158:161], v[122:125]
	v_mfma_f32_16x16x32_bf16 v[118:121], v[138:141], v[162:165], v[118:121]
	v_mfma_f32_16x16x32_bf16 v[118:121], v[142:145], v[170:173], v[118:121]
	v_mfma_f32_16x16x32_bf16 v[114:117], v[146:149], v[162:165], v[114:117]
	v_mfma_f32_16x16x32_bf16 v[114:117], v[150:153], v[170:173], v[114:117]
	v_mfma_f32_16x16x32_bf16 v[110:113], v[138:141], v[174:177], v[110:113]
	v_mfma_f32_16x16x32_bf16 v[110:113], v[142:145], v[178:181], v[110:113]
	v_mfma_f32_16x16x32_bf16 v[106:109], v[146:149], v[174:177], v[106:109]
	v_mfma_f32_16x16x32_bf16 v[106:109], v[150:153], v[178:181], v[106:109]
	v_mfma_f32_16x16x32_bf16 v[102:105], v[138:141], v[182:185], v[102:105]
	v_mfma_f32_16x16x32_bf16 v[102:105], v[142:145], v[186:189], v[102:105]
	v_mfma_f32_16x16x32_bf16 v[98:101], v[146:149], v[182:185], v[98:101]
	v_mfma_f32_16x16x32_bf16 v[98:101], v[150:153], v[186:189], v[98:101]
	s_setprio 0
	s_barrier
	ds_read_b128 v[220:223], v136 offset:16384
	ds_read_b128 v[224:227], v136 offset:17408
	ds_read_b128 v[228:231], v136 offset:18432
	ds_read_b128 v[232:235], v136 offset:19456
	s_barrier
	s_waitcnt lgkmcnt(0)
	s_setprio 1
	v_mfma_f32_16x16x32_bf16 v[94:97], v[220:223], v[154:157], v[94:97]
	v_mfma_f32_16x16x32_bf16 v[94:97], v[224:227], v[158:161], v[94:97]
	v_mfma_f32_16x16x32_bf16 v[90:93], v[228:231], v[154:157], v[90:93]
	v_mfma_f32_16x16x32_bf16 v[90:93], v[232:235], v[158:161], v[90:93]
	v_mfma_f32_16x16x32_bf16 v[86:89], v[220:223], v[162:165], v[86:89]
	v_mfma_f32_16x16x32_bf16 v[86:89], v[224:227], v[170:173], v[86:89]
	v_mfma_f32_16x16x32_bf16 v[82:85], v[228:231], v[162:165], v[82:85]
	v_mfma_f32_16x16x32_bf16 v[82:85], v[232:235], v[170:173], v[82:85]
	v_mfma_f32_16x16x32_bf16 v[78:81], v[220:223], v[174:177], v[78:81]
	v_mfma_f32_16x16x32_bf16 v[78:81], v[224:227], v[178:181], v[78:81]
	v_mfma_f32_16x16x32_bf16 v[74:77], v[228:231], v[174:177], v[74:77]
	v_mfma_f32_16x16x32_bf16 v[74:77], v[232:235], v[178:181], v[74:77]
	v_mfma_f32_16x16x32_bf16 v[70:73], v[220:223], v[182:185], v[70:73]
	v_mfma_f32_16x16x32_bf16 v[70:73], v[224:227], v[186:189], v[70:73]
	v_mfma_f32_16x16x32_bf16 v[66:69], v[228:231], v[182:185], v[66:69]
	v_mfma_f32_16x16x32_bf16 v[66:69], v[232:235], v[186:189], v[66:69]
	s_setprio 0
	s_barrier
; #define WAIT_V(n) asm volatile("s_waitcnt vmcnt(" #n ")" ::: "memory")
; #define WAIT_L(n) asm volatile("s_waitcnt lgkmcnt(" #n ")" ::: "memory")
; #define BAR __builtin_amdgcn_s_barrier()
; #define LDA(dst, b, h)                                                                                   \
;   _Pragma("unroll") for (int m = 0; m < 4; ++m) _Pragma("unroll") for (int k = 0; k < 2; ++k) dst[m][k] = \
;       *reinterpret_cast<const bf16x8*>(aRd + ((b) * 2 + (h)) * 16384 + m * 2048 + k * 1024)
; #define LDB(dst, b, h)                                                                                   \
;   _Pragma("unroll") for (int n = 0; n < 2; ++n) _Pragma("unroll") for (int k = 0; k < 2; ++k) dst[n][k] = \
;       *reinterpret_cast<const bf16x8*>(bRd + ((b) * 2 + (h)) * 16384 + n * 2048 + k * 1024)
; template <int EPI> ...
;     ...
;     LDA(At, 0, 1);
;     WAIT_V(4);
;     BAR;
;     WAIT_L(0);
;     MMA(1, 0, At, B0);
;     MMA(1, 1, At, B1);
;     BAR;
;   }
;   {
;     LDB(B0, 1, 0);
;     LDA(At, 1, 0);
;     WAIT_V(2);
;     BAR;
;     WAIT_L(0);
;     MMA(0, 0, At, B0);
	ds_read_b128 v[154:157], v135 offset:16384
	ds_read_b128 v[158:161], v135 offset:17408
	ds_read_b128 v[162:165], v135 offset:18432
	ds_read_b128 v[170:173], v135 offset:19456
	ds_read_b128 v[174:177], v135 offset:20480
	ds_read_b128 v[178:181], v135 offset:21504
	ds_read_b128 v[182:185], v135 offset:22528
	ds_read_b128 v[186:189], v135 offset:23552
	s_waitcnt vmcnt(4)
	s_barrier
	s_waitcnt lgkmcnt(0)
	s_setprio 1
	v_mfma_f32_16x16x32_bf16 v[62:65], v[138:141], v[154:157], v[62:65]
	v_mfma_f32_16x16x32_bf16 v[62:65], v[142:145], v[158:161], v[62:65]
	v_mfma_f32_16x16x32_bf16 v[58:61], v[146:149], v[154:157], v[58:61]
	v_mfma_f32_16x16x32_bf16 v[58:61], v[150:153], v[158:161], v[58:61]
	v_mfma_f32_16x16x32_bf16 v[54:57], v[138:141], v[162:165], v[54:57]
	v_mfma_f32_16x16x32_bf16 v[54:57], v[142:145], v[170:173], v[54:57]
	v_mfma_f32_16x16x32_bf16 v[50:53], v[146:149], v[162:165], v[50:53]
	v_mfma_f32_16x16x32_bf16 v[50:53], v[150:153], v[170:173], v[50:53]
	v_mfma_f32_16x16x32_bf16 v[46:49], v[138:141], v[174:177], v[46:49]
	v_mfma_f32_16x16x32_bf16 v[46:49], v[142:145], v[178:181], v[46:49]
	v_mfma_f32_16x16x32_bf16 v[42:45], v[146:149], v[174:177], v[42:45]
	v_mfma_f32_16x16x32_bf16 v[42:45], v[150:153], v[178:181], v[42:45]
	v_mfma_f32_16x16x32_bf16 v[38:41], v[138:141], v[182:185], v[38:41]
	v_mfma_f32_16x16x32_bf16 v[38:41], v[142:145], v[186:189], v[38:41]
	v_mfma_f32_16x16x32_bf16 v[34:37], v[146:149], v[182:185], v[34:37]
	v_mfma_f32_16x16x32_bf16 v[34:37], v[150:153], v[186:189], v[34:37]
	s_setprio 0
	s_setprio 1
	v_mfma_f32_16x16x32_bf16 v[30:33], v[220:223], v[154:157], v[30:33]
	v_mfma_f32_16x16x32_bf16 v[30:33], v[224:227], v[158:161], v[30:33]
	v_mfma_f32_16x16x32_bf16 v[26:29], v[228:231], v[154:157], v[26:29]
	v_mfma_f32_16x16x32_bf16 v[26:29], v[232:235], v[158:161], v[26:29]
	v_mfma_f32_16x16x32_bf16 v[22:25], v[220:223], v[162:165], v[22:25]
	v_mfma_f32_16x16x32_bf16 v[22:25], v[224:227], v[170:173], v[22:25]
	v_mfma_f32_16x16x32_bf16 v[18:21], v[228:231], v[162:165], v[18:21]
	v_mfma_f32_16x16x32_bf16 v[18:21], v[232:235], v[170:173], v[18:21]
	v_mfma_f32_16x16x32_bf16 v[14:17], v[220:223], v[174:177], v[14:17]
	v_mfma_f32_16x16x32_bf16 v[14:17], v[224:227], v[178:181], v[14:17]
	v_mfma_f32_16x16x32_bf16 v[10:13], v[228:231], v[174:177], v[10:13]
	v_mfma_f32_16x16x32_bf16 v[10:13], v[232:235], v[178:181], v[10:13]
	v_mfma_f32_16x16x32_bf16 v[6:9], v[220:223], v[182:185], v[6:9]
	v_mfma_f32_16x16x32_bf16 v[6:9], v[224:227], v[186:189], v[6:9]
	v_mfma_f32_16x16x32_bf16 v[2:5], v[228:231], v[182:185], v[2:5]
	v_mfma_f32_16x16x32_bf16 v[2:5], v[232:235], v[186:189], v[2:5]
	s_setprio 0
	s_barrier
	ds_read_b128 v[138:141], v136 offset:32768
	ds_read_b128 v[142:145], v136 offset:33792
	ds_read_b128 v[146:149], v136 offset:34816
	ds_read_b128 v[150:153], v136 offset:35840
	ds_read_b128 v[154:157], v135 offset:32768
	ds_read_b128 v[158:161], v135 offset:33792
	ds_read_b128 v[162:165], v135 offset:34816
	ds_read_b128 v[170:173], v135 offset:35840
	ds_read_b128 v[174:177], v135 offset:36864
	ds_read_b128 v[178:181], v135 offset:37888
	ds_read_b128 v[182:185], v135 offset:38912
	ds_read_b128 v[186:189], v135 offset:39936
	s_waitcnt vmcnt(2)
	s_barrier
	s_waitcnt lgkmcnt(0)
	s_setprio 1
	v_mfma_f32_16x16x32_bf16 v[126:129], v[138:141], v[154:157], v[126:129]
	v_mfma_f32_16x16x32_bf16 v[126:129], v[142:145], v[158:161], v[126:129]
	v_mfma_f32_16x16x32_bf16 v[122:125], v[146:149], v[154:157], v[122:125]
	v_mfma_f32_16x16x32_bf16 v[122:125], v[150:153], v[158:161], v[122:125]
	v_mfma_f32_16x16x32_bf16 v[118:121], v[138:141], v[162:165], v[118:121]
	v_mfma_f32_16x16x32_bf16 v[118:121], v[142:145], v[170:173], v[118:121]
	v_mfma_f32_16x16x32_bf16 v[114:117], v[146:149], v[162:165], v[114:117]
	v_mfma_f32_16x16x32_bf16 v[114:117], v[150:153], v[170:173], v[114:117]
	v_mfma_f32_16x16x32_bf16 v[110:113], v[138:141], v[174:177], v[110:113]
	v_mfma_f32_16x16x32_bf16 v[110:113], v[142:145], v[178:181], v[110:113]
	v_mfma_f32_16x16x32_bf16 v[106:109], v[146:149], v[174:177], v[106:109]
	v_mfma_f32_16x16x32_bf16 v[106:109], v[150:153], v[178:181], v[106:109]
	v_mfma_f32_16x16x32_bf16 v[102:105], v[138:141], v[182:185], v[102:105]
	v_mfma_f32_16x16x32_bf16 v[102:105], v[142:145], v[186:189], v[102:105]
	v_mfma_f32_16x16x32_bf16 v[98:101], v[146:149], v[182:185], v[98:101]
	v_mfma_f32_16x16x32_bf16 v[98:101], v[150:153], v[186:189], v[98:101]
	s_setprio 0
	s_barrier
; #define WAIT_V(n) asm volatile("s_waitcnt vmcnt(" #n ")" ::: "memory")
; #define WAIT_L(n) asm volatile("s_waitcnt lgkmcnt(" #n ")" ::: "memory")
; #define BAR __builtin_amdgcn_s_barrier()
; #define LDA(dst, b, h)                                                                                   \
;   _Pragma("unroll") for (int m = 0; m < 4; ++m) _Pragma("unroll") for (int k = 0; k < 2; ++k) dst[m][k] = \
;       *reinterpret_cast<const bf16x8*>(aRd + ((b) * 2 + (h)) * 16384 + m * 2048 + k * 1024)
; #define LDB(dst, b, h)                                                                                   \
;   _Pragma("unroll") for (int n = 0; n < 2; ++n) _Pragma("unroll") for (int k = 0; k < 2; ++k) dst[n][k] = \
;       *reinterpret_cast<const bf16x8*>(bRd + ((b) * 2 + (h)) * 16384 + n * 2048 + k * 1024)
; template <int EPI> ...
;     ...
;     BAR;
;     LDB(B1, 1, 1);
;     WAIT_V(0);
;     BAR;
;     WAIT_L(0);
;     MMA(0, 1, At, B1);
;     BAR;
;     LDA(At, 1, 1);
;     BAR;
;     WAIT_L(0);
;     MMA(1, 0, At, B0);
;     MMA(1, 1, At, B1);
;     BAR;
;   }
;   if (wr == 0) BAR;
;   if (nAb) {
	ds_read_b128 v[220:223], v136 offset:49152
	ds_read_b128 v[224:227], v136 offset:50176
	ds_read_b128 v[228:231], v136 offset:51200
	ds_read_b128 v[232:235], v136 offset:52224
	s_waitcnt vmcnt(0)
	s_barrier
	s_waitcnt lgkmcnt(0)
	s_setprio 1
	v_mfma_f32_16x16x32_bf16 v[94:97], v[220:223], v[154:157], v[94:97]
	v_mfma_f32_16x16x32_bf16 v[94:97], v[224:227], v[158:161], v[94:97]
	v_mfma_f32_16x16x32_bf16 v[90:93], v[228:231], v[154:157], v[90:93]
	v_mfma_f32_16x16x32_bf16 v[90:93], v[232:235], v[158:161], v[90:93]
	v_mfma_f32_16x16x32_bf16 v[86:89], v[220:223], v[162:165], v[86:89]
	v_mfma_f32_16x16x32_bf16 v[86:89], v[224:227], v[170:173], v[86:89]
	v_mfma_f32_16x16x32_bf16 v[82:85], v[228:231], v[162:165], v[82:85]
	v_mfma_f32_16x16x32_bf16 v[82:85], v[232:235], v[170:173], v[82:85]
	v_mfma_f32_16x16x32_bf16 v[78:81], v[220:223], v[174:177], v[78:81]
	v_mfma_f32_16x16x32_bf16 v[78:81], v[224:227], v[178:181], v[78:81]
	v_mfma_f32_16x16x32_bf16 v[74:77], v[228:231], v[174:177], v[74:77]
	v_mfma_f32_16x16x32_bf16 v[74:77], v[232:235], v[178:181], v[74:77]
	v_mfma_f32_16x16x32_bf16 v[70:73], v[220:223], v[182:185], v[70:73]
	v_mfma_f32_16x16x32_bf16 v[70:73], v[224:227], v[186:189], v[70:73]
	v_mfma_f32_16x16x32_bf16 v[66:69], v[228:231], v[182:185], v[66:69]
	v_mfma_f32_16x16x32_bf16 v[66:69], v[232:235], v[186:189], v[66:69]
	s_setprio 0
	s_barrier
	ds_read_b128 v[154:157], v135 offset:49152
	ds_read_b128 v[158:161], v135 offset:50176
	ds_read_b128 v[162:165], v135 offset:51200
	ds_read_b128 v[170:173], v135 offset:52224
	ds_read_b128 v[174:177], v135 offset:53248
	ds_read_b128 v[178:181], v135 offset:54272
	ds_read_b128 v[182:185], v135 offset:55296
	ds_read_b128 v[186:189], v135 offset:56320
	s_barrier
	s_waitcnt lgkmcnt(0)
	s_setprio 1
	v_mfma_f32_16x16x32_bf16 v[62:65], v[138:141], v[154:157], v[62:65]
	v_mfma_f32_16x16x32_bf16 v[62:65], v[142:145], v[158:161], v[62:65]
	v_mfma_f32_16x16x32_bf16 v[58:61], v[146:149], v[154:157], v[58:61]
	v_mfma_f32_16x16x32_bf16 v[58:61], v[150:153], v[158:161], v[58:61]
	v_mfma_f32_16x16x32_bf16 v[54:57], v[138:141], v[162:165], v[54:57]
	v_mfma_f32_16x16x32_bf16 v[54:57], v[142:145], v[170:173], v[54:57]
	v_mfma_f32_16x16x32_bf16 v[50:53], v[146:149], v[162:165], v[50:53]
	v_mfma_f32_16x16x32_bf16 v[50:53], v[150:153], v[170:173], v[50:53]
	v_mfma_f32_16x16x32_bf16 v[46:49], v[138:141], v[174:177], v[46:49]
	v_mfma_f32_16x16x32_bf16 v[46:49], v[142:145], v[178:181], v[46:49]
	v_mfma_f32_16x16x32_bf16 v[42:45], v[146:149], v[174:177], v[42:45]
	v_mfma_f32_16x16x32_bf16 v[42:45], v[150:153], v[178:181], v[42:45]
	v_mfma_f32_16x16x32_bf16 v[38:41], v[138:141], v[182:185], v[38:41]
	v_mfma_f32_16x16x32_bf16 v[38:41], v[142:145], v[186:189], v[38:41]
	v_mfma_f32_16x16x32_bf16 v[34:37], v[146:149], v[182:185], v[34:37]
	v_mfma_f32_16x16x32_bf16 v[34:37], v[150:153], v[186:189], v[34:37]
	s_setprio 0
	s_setprio 1
	v_mfma_f32_16x16x32_bf16 v[30:33], v[220:223], v[154:157], v[30:33]
	v_mfma_f32_16x16x32_bf16 v[30:33], v[224:227], v[158:161], v[30:33]
	v_mfma_f32_16x16x32_bf16 v[26:29], v[228:231], v[154:157], v[26:29]
	v_mfma_f32_16x16x32_bf16 v[26:29], v[232:235], v[158:161], v[26:29]
	v_mfma_f32_16x16x32_bf16 v[22:25], v[220:223], v[162:165], v[22:25]
	v_mfma_f32_16x16x32_bf16 v[22:25], v[224:227], v[170:173], v[22:25]
	v_mfma_f32_16x16x32_bf16 v[18:21], v[228:231], v[162:165], v[18:21]
	v_mfma_f32_16x16x32_bf16 v[18:21], v[232:235], v[170:173], v[18:21]
	v_mfma_f32_16x16x32_bf16 v[14:17], v[220:223], v[174:177], v[14:17]
	v_mfma_f32_16x16x32_bf16 v[14:17], v[224:227], v[178:181], v[14:17]
	v_mfma_f32_16x16x32_bf16 v[10:13], v[228:231], v[174:177], v[10:13]
	v_mfma_f32_16x16x32_bf16 v[10:13], v[232:235], v[178:181], v[10:13]
	v_mfma_f32_16x16x32_bf16 v[6:9], v[220:223], v[182:185], v[6:9]
	v_mfma_f32_16x16x32_bf16 v[6:9], v[224:227], v[186:189], v[6:9]
	v_mfma_f32_16x16x32_bf16 v[2:5], v[228:231], v[182:185], v[2:5]
	v_mfma_f32_16x16x32_bf16 v[2:5], v[232:235], v[186:189], v[2:5]
	s_setprio 0
	s_movk_i32 s6, 0x100
	v_cmp_gt_u32_e32 vcc, s6, v133
	s_barrier
	s_and_saveexec_b64 s[12:13], vcc
	s_cbranch_execz .LBB0_418
	s_barrier
